# v46 + s_setprio 2/0 around the ds_read_b128 burst of each K-loop load segment + redundant post-barrier lgkmcnt(0) dropped at the 36 MFMA block heads
# baseline (speedup 1.0000x reference)
.LBB0_577:
	s_setprio 2
	ds_read_b128 v[128:131], v193
	ds_read_b128 v[132:135], v193 offset:1024
	ds_read_b128 v[136:139], v193 offset:2048
	ds_read_b128 v[140:143], v193 offset:3072
	ds_read_b128 v[144:147], v194
	ds_read_b128 v[148:151], v194 offset:1024
	ds_read_b128 v[152:155], v194 offset:2048
	ds_read_b128 v[156:159], v194 offset:3072
	s_add_u32 s35, s42, 0xfff80080
	s_addc_u32 s39, s43, -1
	s_cmp_eq_u32 s31, 4
	s_cselect_b32 s47, s1, s39
	s_cselect_b32 s46, s0, s35
	s_cselect_b32 s45, s37, s23
	s_cselect_b32 s44, s36, s11
	v_lshl_add_u64 v[218:219], s[42:43], 0, v[168:169]
	s_add_i32 m0, s7, 0xc000
	ds_read_b128 v[176:179], v195
	ds_read_b128 v[180:183], v195 offset:1024
	ds_read_b128 v[184:187], v195 offset:2048
	ds_read_b128 v[198:201], v195 offset:3072
	ds_read_b128 v[202:205], v195 offset:4096
	ds_read_b128 v[206:209], v195 offset:5120
	ds_read_b128 v[210:213], v195 offset:6144
	ds_read_b128 v[214:217], v195 offset:7168
	s_setprio 0
	global_load_lds_dwordx4 v[218:219], off
	v_lshl_add_u64 v[218:219], s[42:43], 0, v[170:171]
	s_add_i32 m0, s7, 0xe000
	s_nop 0
	global_load_lds_dwordx4 v[218:219], off
	s_waitcnt vmcnt(8)
	s_waitcnt lgkmcnt(0)
	s_barrier
	v_mfma_f32_16x16x32_bf16 v[124:127], v[128:131], v[176:179], v[124:127]
	v_mfma_f32_16x16x32_bf16 v[120:123], v[136:139], v[176:179], v[120:123]
	v_mfma_f32_16x16x32_bf16 v[108:111], v[128:131], v[184:187], v[108:111]
	v_mfma_f32_16x16x32_bf16 v[104:107], v[136:139], v[184:187], v[104:107]
	v_mfma_f32_16x16x32_bf16 v[92:95], v[128:131], v[202:205], v[92:95]
	v_mfma_f32_16x16x32_bf16 v[88:91], v[136:139], v[202:205], v[88:91]
	v_mfma_f32_16x16x32_bf16 v[76:79], v[128:131], v[210:213], v[76:79]
	v_mfma_f32_16x16x32_bf16 v[72:75], v[136:139], v[210:213], v[72:75]
	v_mfma_f32_16x16x32_bf16 v[124:127], v[132:135], v[180:183], v[124:127]
	v_mfma_f32_16x16x32_bf16 v[120:123], v[140:143], v[180:183], v[120:123]
	v_mfma_f32_16x16x32_bf16 v[108:111], v[132:135], v[198:201], v[108:111]
	v_mfma_f32_16x16x32_bf16 v[104:107], v[140:143], v[198:201], v[104:107]
	v_mfma_f32_16x16x32_bf16 v[92:95], v[132:135], v[206:209], v[92:95]
	v_mfma_f32_16x16x32_bf16 v[88:91], v[140:143], v[206:209], v[88:91]
	v_mfma_f32_16x16x32_bf16 v[76:79], v[132:135], v[214:217], v[76:79]
	v_mfma_f32_16x16x32_bf16 v[72:75], v[140:143], v[214:217], v[72:75]
	v_mfma_f32_16x16x32_bf16 v[116:119], v[144:147], v[176:179], v[116:119]
	v_mfma_f32_16x16x32_bf16 v[112:115], v[152:155], v[176:179], v[112:115]
	v_mfma_f32_16x16x32_bf16 v[100:103], v[144:147], v[184:187], v[100:103]
	v_mfma_f32_16x16x32_bf16 v[96:99], v[152:155], v[184:187], v[96:99]
	v_mfma_f32_16x16x32_bf16 v[84:87], v[144:147], v[202:205], v[84:87]
	v_mfma_f32_16x16x32_bf16 v[80:83], v[152:155], v[202:205], v[80:83]
	v_mfma_f32_16x16x32_bf16 v[68:71], v[144:147], v[210:213], v[68:71]
	v_mfma_f32_16x16x32_bf16 v[64:67], v[152:155], v[210:213], v[64:67]
	v_mfma_f32_16x16x32_bf16 v[116:119], v[148:151], v[180:183], v[116:119]
	v_mfma_f32_16x16x32_bf16 v[112:115], v[156:159], v[180:183], v[112:115]
	v_mfma_f32_16x16x32_bf16 v[100:103], v[148:151], v[198:201], v[100:103]
	v_mfma_f32_16x16x32_bf16 v[96:99], v[156:159], v[198:201], v[96:99]
	v_mfma_f32_16x16x32_bf16 v[84:87], v[148:151], v[206:209], v[84:87]
	v_mfma_f32_16x16x32_bf16 v[80:83], v[156:159], v[206:209], v[80:83]
	v_mfma_f32_16x16x32_bf16 v[68:71], v[148:151], v[214:217], v[68:71]
	v_mfma_f32_16x16x32_bf16 v[64:67], v[156:159], v[214:217], v[64:67]
	s_barrier
	s_add_i32 s35, s48, s6
	v_lshl_add_u64 v[218:219], s[44:45], 0, v[162:163]
	s_mov_b32 m0, s35
	s_setprio 2
	ds_read_b128 v[176:179], v195 offset:16384
	ds_read_b128 v[180:183], v195 offset:17408
	ds_read_b128 v[184:187], v195 offset:18432
	ds_read_b128 v[198:201], v195 offset:19456
	ds_read_b128 v[202:205], v195 offset:20480
	ds_read_b128 v[206:209], v195 offset:21504
	ds_read_b128 v[210:213], v195 offset:22528
	ds_read_b128 v[214:217], v195 offset:23552
	s_setprio 0
	global_load_lds_dwordx4 v[218:219], off
	s_add_i32 m0, s35, 0x2000
	s_add_u32 s50, s44, 0x20000
	v_lshl_add_u64 v[220:221], s[44:45], 0, v[166:167]
	s_addc_u32 s51, s45, 0
	s_add_i32 s35, s49, s6
	global_load_lds_dwordx4 v[220:221], off
	v_lshl_add_u64 v[222:223], s[50:51], 0, v[162:163]
	s_mov_b32 m0, s35
	v_lshl_add_u64 v[224:225], s[46:47], 0, v[164:165]
	global_load_lds_dwordx4 v[222:223], off
	v_lshl_add_u64 v[222:223], s[50:51], 0, v[166:167]
	s_add_i32 m0, s35, 0x2000
	s_nop 0
	global_load_lds_dwordx4 v[222:223], off
	v_lshl_add_u64 v[222:223], s[46:47], 0, v[160:161]
	s_mov_b32 m0, s7
	s_nop 0
	global_load_lds_dwordx4 v[222:223], off
	s_mov_b32 m0, s8
	s_nop 0
	global_load_lds_dwordx4 v[224:225], off
	s_waitcnt vmcnt(8)
	s_waitcnt lgkmcnt(0)
	s_barrier
	v_mfma_f32_16x16x32_bf16 v[60:63], v[128:131], v[176:179], v[60:63]
	v_mfma_f32_16x16x32_bf16 v[56:59], v[136:139], v[176:179], v[56:59]
	v_mfma_f32_16x16x32_bf16 v[44:47], v[128:131], v[184:187], v[44:47]
	v_mfma_f32_16x16x32_bf16 v[40:43], v[136:139], v[184:187], v[40:43]
	v_mfma_f32_16x16x32_bf16 v[28:31], v[128:131], v[202:205], v[28:31]
	v_mfma_f32_16x16x32_bf16 v[24:27], v[136:139], v[202:205], v[24:27]
	v_mfma_f32_16x16x32_bf16 v[12:15], v[128:131], v[210:213], v[12:15]
	v_mfma_f32_16x16x32_bf16 v[8:11], v[136:139], v[210:213], v[8:11]
	v_mfma_f32_16x16x32_bf16 v[60:63], v[132:135], v[180:183], v[60:63]
	v_mfma_f32_16x16x32_bf16 v[56:59], v[140:143], v[180:183], v[56:59]
	v_mfma_f32_16x16x32_bf16 v[44:47], v[132:135], v[198:201], v[44:47]
	v_mfma_f32_16x16x32_bf16 v[40:43], v[140:143], v[198:201], v[40:43]
	v_mfma_f32_16x16x32_bf16 v[28:31], v[132:135], v[206:209], v[28:31]
	v_mfma_f32_16x16x32_bf16 v[24:27], v[140:143], v[206:209], v[24:27]
	v_mfma_f32_16x16x32_bf16 v[12:15], v[132:135], v[214:217], v[12:15]
	v_mfma_f32_16x16x32_bf16 v[8:11], v[140:143], v[214:217], v[8:11]
	v_mfma_f32_16x16x32_bf16 v[52:55], v[144:147], v[176:179], v[52:55]
	v_mfma_f32_16x16x32_bf16 v[48:51], v[152:155], v[176:179], v[48:51]
	v_mfma_f32_16x16x32_bf16 v[36:39], v[144:147], v[184:187], v[36:39]
	v_mfma_f32_16x16x32_bf16 v[32:35], v[152:155], v[184:187], v[32:35]
	v_mfma_f32_16x16x32_bf16 v[20:23], v[144:147], v[202:205], v[20:23]
	v_mfma_f32_16x16x32_bf16 v[16:19], v[152:155], v[202:205], v[16:19]
	v_mfma_f32_16x16x32_bf16 v[4:7], v[144:147], v[210:213], v[4:7]
	v_mfma_f32_16x16x32_bf16 v[0:3], v[152:155], v[210:213], v[0:3]
	v_mfma_f32_16x16x32_bf16 v[52:55], v[148:151], v[180:183], v[52:55]
	v_mfma_f32_16x16x32_bf16 v[48:51], v[156:159], v[180:183], v[48:51]
	v_mfma_f32_16x16x32_bf16 v[36:39], v[148:151], v[198:201], v[36:39]
	v_mfma_f32_16x16x32_bf16 v[32:35], v[156:159], v[198:201], v[32:35]
	v_mfma_f32_16x16x32_bf16 v[20:23], v[148:151], v[206:209], v[20:23]
	v_mfma_f32_16x16x32_bf16 v[16:19], v[156:159], v[206:209], v[16:19]
	v_mfma_f32_16x16x32_bf16 v[4:7], v[148:151], v[214:217], v[4:7]
	v_mfma_f32_16x16x32_bf16 v[0:3], v[156:159], v[214:217], v[0:3]
	s_barrier
	s_add_i32 s35, 0, 0x18000
	s_add_i32 s39, 0, 0x1c000
	v_add_u32_e32 v140, s35, v191
	v_add_u32_e32 v156, s39, v191
	s_setprio 2
	ds_read_b128 v[128:131], v140
	ds_read_b128 v[132:135], v140 offset:1024
	ds_read_b128 v[136:139], v140 offset:2048
	ds_read_b128 v[140:143], v140 offset:3072
	ds_read_b128 v[144:147], v156
	ds_read_b128 v[148:151], v156 offset:1024
	ds_read_b128 v[152:155], v156 offset:2048
	ds_read_b128 v[156:159], v156 offset:3072
	s_add_u32 s46, s46, 0x80000
	s_addc_u32 s47, s47, 0
	s_mov_b32 m0, s9
	v_lshl_add_u64 v[226:227], s[46:47], 0, v[160:161]
	ds_read_b128 v[176:179], v195 offset:32768
	ds_read_b128 v[180:183], v195 offset:33792
	ds_read_b128 v[184:187], v195 offset:34816
	ds_read_b128 v[198:201], v195 offset:35840
	ds_read_b128 v[202:205], v195 offset:36864
	ds_read_b128 v[206:209], v195 offset:37888
	ds_read_b128 v[210:213], v195 offset:38912
	ds_read_b128 v[214:217], v195 offset:39936
	s_setprio 0
	global_load_lds_dwordx4 v[226:227], off
	v_lshl_add_u64 v[226:227], s[46:47], 0, v[164:165]
	s_mov_b32 m0, s24
	s_nop 0
	global_load_lds_dwordx4 v[226:227], off
	s_waitcnt vmcnt(8)
	s_waitcnt lgkmcnt(0)
	s_barrier
	v_mfma_f32_16x16x32_bf16 v[124:127], v[128:131], v[176:179], v[124:127]
	v_mfma_f32_16x16x32_bf16 v[120:123], v[136:139], v[176:179], v[120:123]
	v_mfma_f32_16x16x32_bf16 v[108:111], v[128:131], v[184:187], v[108:111]
	v_mfma_f32_16x16x32_bf16 v[104:107], v[136:139], v[184:187], v[104:107]
	v_mfma_f32_16x16x32_bf16 v[92:95], v[128:131], v[202:205], v[92:95]
	v_mfma_f32_16x16x32_bf16 v[88:91], v[136:139], v[202:205], v[88:91]
	v_mfma_f32_16x16x32_bf16 v[76:79], v[128:131], v[210:213], v[76:79]
	v_mfma_f32_16x16x32_bf16 v[72:75], v[136:139], v[210:213], v[72:75]
	v_mfma_f32_16x16x32_bf16 v[124:127], v[132:135], v[180:183], v[124:127]
	v_mfma_f32_16x16x32_bf16 v[120:123], v[140:143], v[180:183], v[120:123]
	v_mfma_f32_16x16x32_bf16 v[108:111], v[132:135], v[198:201], v[108:111]
	v_mfma_f32_16x16x32_bf16 v[104:107], v[140:143], v[198:201], v[104:107]
	v_mfma_f32_16x16x32_bf16 v[92:95], v[132:135], v[206:209], v[92:95]
	v_mfma_f32_16x16x32_bf16 v[88:91], v[140:143], v[206:209], v[88:91]
	v_mfma_f32_16x16x32_bf16 v[76:79], v[132:135], v[214:217], v[76:79]
	v_mfma_f32_16x16x32_bf16 v[72:75], v[140:143], v[214:217], v[72:75]
	v_mfma_f32_16x16x32_bf16 v[116:119], v[144:147], v[176:179], v[116:119]
	v_mfma_f32_16x16x32_bf16 v[112:115], v[152:155], v[176:179], v[112:115]
	v_mfma_f32_16x16x32_bf16 v[100:103], v[144:147], v[184:187], v[100:103]
	v_mfma_f32_16x16x32_bf16 v[96:99], v[152:155], v[184:187], v[96:99]
	v_mfma_f32_16x16x32_bf16 v[84:87], v[144:147], v[202:205], v[84:87]
	v_mfma_f32_16x16x32_bf16 v[80:83], v[152:155], v[202:205], v[80:83]
	v_mfma_f32_16x16x32_bf16 v[68:71], v[144:147], v[210:213], v[68:71]
	v_mfma_f32_16x16x32_bf16 v[64:67], v[152:155], v[210:213], v[64:67]
	v_mfma_f32_16x16x32_bf16 v[116:119], v[148:151], v[180:183], v[116:119]
	v_mfma_f32_16x16x32_bf16 v[112:115], v[156:159], v[180:183], v[112:115]
	v_mfma_f32_16x16x32_bf16 v[100:103], v[148:151], v[198:201], v[100:103]
	v_mfma_f32_16x16x32_bf16 v[96:99], v[156:159], v[198:201], v[96:99]
	v_mfma_f32_16x16x32_bf16 v[84:87], v[148:151], v[206:209], v[84:87]
	v_mfma_f32_16x16x32_bf16 v[80:83], v[156:159], v[206:209], v[80:83]
	v_mfma_f32_16x16x32_bf16 v[68:71], v[148:151], v[214:217], v[68:71]
	v_mfma_f32_16x16x32_bf16 v[64:67], v[156:159], v[214:217], v[64:67]
	s_barrier
	s_add_i32 s35, s35, s6
	v_lshl_add_u64 v[218:219], v[218:219], 0, s[16:17]
	s_mov_b32 m0, s35
	s_setprio 2
	ds_read_b128 v[176:179], v195 offset:49152
	ds_read_b128 v[180:183], v195 offset:50176
	ds_read_b128 v[184:187], v195 offset:51200
	ds_read_b128 v[198:201], v195 offset:52224
	ds_read_b128 v[202:205], v195 offset:53248
	ds_read_b128 v[206:209], v195 offset:54272
	ds_read_b128 v[210:213], v195 offset:55296
	ds_read_b128 v[214:217], v195 offset:56320
	s_setprio 0
	global_load_lds_dwordx4 v[218:219], off
	s_add_i32 m0, s35, 0x2000
	s_add_u32 s44, s44, 0x20080
	v_lshl_add_u64 v[218:219], v[220:221], 0, s[16:17]
	s_addc_u32 s45, s45, 0
	s_add_i32 s35, s39, s6
	global_load_lds_dwordx4 v[218:219], off
	v_lshl_add_u64 v[218:219], s[44:45], 0, v[162:163]
	s_mov_b32 m0, s35
	s_nop 0
	global_load_lds_dwordx4 v[218:219], off
	v_lshl_add_u64 v[218:219], s[44:45], 0, v[166:167]
	s_add_i32 m0, s35, 0x2000
	s_nop 0
	global_load_lds_dwordx4 v[218:219], off
	v_lshl_add_u64 v[218:219], v[222:223], 0, s[16:17]
	s_mov_b32 m0, s28
	s_nop 0
	global_load_lds_dwordx4 v[218:219], off
	v_lshl_add_u64 v[218:219], v[224:225], 0, s[16:17]
	s_mov_b32 m0, s29
	s_nop 0
	global_load_lds_dwordx4 v[218:219], off
	s_waitcnt vmcnt(8)
	s_waitcnt lgkmcnt(0)
	s_barrier
	v_mfma_f32_16x16x32_bf16 v[60:63], v[128:131], v[176:179], v[60:63]
	v_mfma_f32_16x16x32_bf16 v[56:59], v[136:139], v[176:179], v[56:59]
	v_mfma_f32_16x16x32_bf16 v[44:47], v[128:131], v[184:187], v[44:47]
	v_mfma_f32_16x16x32_bf16 v[40:43], v[136:139], v[184:187], v[40:43]
	v_mfma_f32_16x16x32_bf16 v[28:31], v[128:131], v[202:205], v[28:31]
	v_mfma_f32_16x16x32_bf16 v[24:27], v[136:139], v[202:205], v[24:27]
	v_mfma_f32_16x16x32_bf16 v[12:15], v[128:131], v[210:213], v[12:15]
	v_mfma_f32_16x16x32_bf16 v[8:11], v[136:139], v[210:213], v[8:11]
	v_mfma_f32_16x16x32_bf16 v[60:63], v[132:135], v[180:183], v[60:63]
	v_mfma_f32_16x16x32_bf16 v[56:59], v[140:143], v[180:183], v[56:59]
	v_mfma_f32_16x16x32_bf16 v[44:47], v[132:135], v[198:201], v[44:47]
	v_mfma_f32_16x16x32_bf16 v[40:43], v[140:143], v[198:201], v[40:43]
	v_mfma_f32_16x16x32_bf16 v[28:31], v[132:135], v[206:209], v[28:31]
	v_mfma_f32_16x16x32_bf16 v[24:27], v[140:143], v[206:209], v[24:27]
	v_mfma_f32_16x16x32_bf16 v[12:15], v[132:135], v[214:217], v[12:15]
	v_mfma_f32_16x16x32_bf16 v[8:11], v[140:143], v[214:217], v[8:11]
	v_mfma_f32_16x16x32_bf16 v[52:55], v[144:147], v[176:179], v[52:55]
	v_mfma_f32_16x16x32_bf16 v[48:51], v[152:155], v[176:179], v[48:51]
	v_mfma_f32_16x16x32_bf16 v[36:39], v[144:147], v[184:187], v[36:39]
	v_mfma_f32_16x16x32_bf16 v[32:35], v[152:155], v[184:187], v[32:35]
	v_mfma_f32_16x16x32_bf16 v[20:23], v[144:147], v[202:205], v[20:23]
	v_mfma_f32_16x16x32_bf16 v[16:19], v[152:155], v[202:205], v[16:19]
	v_mfma_f32_16x16x32_bf16 v[4:7], v[144:147], v[210:213], v[4:7]
	v_mfma_f32_16x16x32_bf16 v[0:3], v[152:155], v[210:213], v[0:3]
	v_mfma_f32_16x16x32_bf16 v[52:55], v[148:151], v[180:183], v[52:55]
	v_mfma_f32_16x16x32_bf16 v[48:51], v[156:159], v[180:183], v[48:51]
	v_mfma_f32_16x16x32_bf16 v[36:39], v[148:151], v[198:201], v[36:39]
	v_mfma_f32_16x16x32_bf16 v[32:35], v[156:159], v[198:201], v[32:35]
	v_mfma_f32_16x16x32_bf16 v[20:23], v[148:151], v[206:209], v[20:23]
	v_mfma_f32_16x16x32_bf16 v[16:19], v[156:159], v[206:209], v[16:19]
	v_mfma_f32_16x16x32_bf16 v[4:7], v[148:151], v[214:217], v[4:7]
	v_mfma_f32_16x16x32_bf16 v[0:3], v[156:159], v[214:217], v[0:3]
	s_barrier
	s_add_i32 s31, s31, 2
	s_add_u32 s42, s42, 0x100
	s_addc_u32 s43, s43, 0
	s_add_u32 s11, s11, 0x100
	s_addc_u32 s23, s23, 0
	s_cmp_gt_u32 s31, 5
	s_cbranch_scc0 .LBB0_577
	s_and_b64 vcc, exec, s[18:19]
	s_cbranch_vccz .LBB0_580
	s_barrier

.LBB0_664:
	s_setprio 2
	ds_read_b128 v[156:159], v151
	ds_read_b128 v[160:163], v151 offset:1024
	ds_read_b128 v[164:167], v151 offset:2048
	ds_read_b128 v[168:171], v151 offset:3072
	ds_read_b128 v[172:175], v152
	ds_read_b128 v[176:179], v152 offset:1024
	ds_read_b128 v[180:183], v152 offset:2048
	ds_read_b128 v[184:187], v152 offset:3072
	s_add_u32 s22, s20, 0xfff80080
	s_addc_u32 s23, s21, -1
	s_cmp_eq_u32 s48, 28
	s_cselect_b32 s31, s13, s23
	s_cselect_b32 s30, s44, s22
	s_cselect_b32 s23, s15, s47
	s_cselect_b32 s22, s45, s46
	v_lshl_add_u64 v[146:147], s[20:21], 0, v[138:139]
	s_add_i32 m0, s11, 0xc000
	ds_read_b128 v[190:193], v153
	ds_read_b128 v[194:197], v153 offset:1024
	ds_read_b128 v[198:201], v153 offset:2048
	ds_read_b128 v[202:205], v153 offset:3072
	ds_read_b128 v[206:209], v153 offset:4096
	ds_read_b128 v[210:213], v153 offset:5120
	ds_read_b128 v[214:217], v153 offset:6144
	ds_read_b128 v[218:221], v153 offset:7168
	s_setprio 0
	global_load_lds_dwordx4 v[146:147], off
	v_lshl_add_u64 v[146:147], s[20:21], 0, v[140:141]
	s_add_i32 m0, s11, 0xe000
	s_nop 0
	global_load_lds_dwordx4 v[146:147], off
	s_waitcnt vmcnt(8)
	s_waitcnt lgkmcnt(0)
	s_barrier
	v_mfma_f32_16x16x32_bf16 v[116:119], v[156:159], v[190:193], v[116:119]
	v_mfma_f32_16x16x32_bf16 v[112:115], v[164:167], v[190:193], v[112:115]
	v_mfma_f32_16x16x32_bf16 v[100:103], v[156:159], v[198:201], v[100:103]
	v_mfma_f32_16x16x32_bf16 v[96:99], v[164:167], v[198:201], v[96:99]
	v_mfma_f32_16x16x32_bf16 v[84:87], v[156:159], v[206:209], v[84:87]
	v_mfma_f32_16x16x32_bf16 v[80:83], v[164:167], v[206:209], v[80:83]
	v_mfma_f32_16x16x32_bf16 v[68:71], v[156:159], v[214:217], v[68:71]
	v_mfma_f32_16x16x32_bf16 v[64:67], v[164:167], v[214:217], v[64:67]
	v_mfma_f32_16x16x32_bf16 v[116:119], v[160:163], v[194:197], v[116:119]
	v_mfma_f32_16x16x32_bf16 v[112:115], v[168:171], v[194:197], v[112:115]
	v_mfma_f32_16x16x32_bf16 v[100:103], v[160:163], v[202:205], v[100:103]
	v_mfma_f32_16x16x32_bf16 v[96:99], v[168:171], v[202:205], v[96:99]
	v_mfma_f32_16x16x32_bf16 v[84:87], v[160:163], v[210:213], v[84:87]
	v_mfma_f32_16x16x32_bf16 v[80:83], v[168:171], v[210:213], v[80:83]
	v_mfma_f32_16x16x32_bf16 v[68:71], v[160:163], v[218:221], v[68:71]
	v_mfma_f32_16x16x32_bf16 v[64:67], v[168:171], v[218:221], v[64:67]
	v_mfma_f32_16x16x32_bf16 v[124:127], v[172:175], v[190:193], v[124:127]
	v_mfma_f32_16x16x32_bf16 v[120:123], v[180:183], v[190:193], v[120:123]
	v_mfma_f32_16x16x32_bf16 v[108:111], v[172:175], v[198:201], v[108:111]
	v_mfma_f32_16x16x32_bf16 v[104:107], v[180:183], v[198:201], v[104:107]
	v_mfma_f32_16x16x32_bf16 v[92:95], v[172:175], v[206:209], v[92:95]
	v_mfma_f32_16x16x32_bf16 v[88:91], v[180:183], v[206:209], v[88:91]
	v_mfma_f32_16x16x32_bf16 v[76:79], v[172:175], v[214:217], v[76:79]
	v_mfma_f32_16x16x32_bf16 v[72:75], v[180:183], v[214:217], v[72:75]
	v_mfma_f32_16x16x32_bf16 v[124:127], v[176:179], v[194:197], v[124:127]
	v_mfma_f32_16x16x32_bf16 v[120:123], v[184:187], v[194:197], v[120:123]
	v_mfma_f32_16x16x32_bf16 v[108:111], v[176:179], v[202:205], v[108:111]
	v_mfma_f32_16x16x32_bf16 v[104:107], v[184:187], v[202:205], v[104:107]
	v_mfma_f32_16x16x32_bf16 v[92:95], v[176:179], v[210:213], v[92:95]
	v_mfma_f32_16x16x32_bf16 v[88:91], v[184:187], v[210:213], v[88:91]
	v_mfma_f32_16x16x32_bf16 v[76:79], v[176:179], v[218:221], v[76:79]
	v_mfma_f32_16x16x32_bf16 v[72:75], v[184:187], v[218:221], v[72:75]
	s_barrier
	s_add_i32 s49, s40, s26
	v_lshl_add_u64 v[146:147], s[22:23], 0, v[130:131]
	s_mov_b32 m0, s49
	s_setprio 2
	ds_read_b128 v[190:193], v153 offset:16384
	ds_read_b128 v[194:197], v153 offset:17408
	ds_read_b128 v[198:201], v153 offset:18432
	ds_read_b128 v[202:205], v153 offset:19456
	ds_read_b128 v[206:209], v153 offset:20480
	ds_read_b128 v[210:213], v153 offset:21504
	ds_read_b128 v[214:217], v153 offset:22528
	ds_read_b128 v[218:221], v153 offset:23552
	s_setprio 0
	global_load_lds_dwordx4 v[146:147], off
	s_add_i32 m0, s49, 0x2000
	s_add_u32 s50, s22, 0x80000
	v_lshl_add_u64 v[222:223], s[22:23], 0, v[134:135]
	s_addc_u32 s51, s23, 0
	s_add_i32 s49, s41, s26
	global_load_lds_dwordx4 v[222:223], off
	v_lshl_add_u64 v[224:225], s[50:51], 0, v[130:131]
	s_mov_b32 m0, s49
	v_lshl_add_u64 v[226:227], s[30:31], 0, v[132:133]
	global_load_lds_dwordx4 v[224:225], off
	v_lshl_add_u64 v[224:225], s[50:51], 0, v[134:135]
	s_add_i32 m0, s49, 0x2000
	s_nop 0
	global_load_lds_dwordx4 v[224:225], off
	v_lshl_add_u64 v[224:225], s[30:31], 0, v[128:129]
	s_mov_b32 m0, s11
	s_nop 0
	global_load_lds_dwordx4 v[224:225], off
	s_mov_b32 m0, s28
	s_nop 0
	global_load_lds_dwordx4 v[226:227], off
	s_waitcnt vmcnt(8)
	s_waitcnt lgkmcnt(0)
	s_barrier
	v_mfma_f32_16x16x32_bf16 v[52:55], v[156:159], v[190:193], v[52:55]
	v_mfma_f32_16x16x32_bf16 v[48:51], v[164:167], v[190:193], v[48:51]
	v_mfma_f32_16x16x32_bf16 v[36:39], v[156:159], v[198:201], v[36:39]
	v_mfma_f32_16x16x32_bf16 v[32:35], v[164:167], v[198:201], v[32:35]
	v_mfma_f32_16x16x32_bf16 v[20:23], v[156:159], v[206:209], v[20:23]
	v_mfma_f32_16x16x32_bf16 v[16:19], v[164:167], v[206:209], v[16:19]
	v_mfma_f32_16x16x32_bf16 v[8:11], v[156:159], v[214:217], v[8:11]
	v_mfma_f32_16x16x32_bf16 v[0:3], v[164:167], v[214:217], v[0:3]
	v_mfma_f32_16x16x32_bf16 v[52:55], v[160:163], v[194:197], v[52:55]
	v_mfma_f32_16x16x32_bf16 v[48:51], v[168:171], v[194:197], v[48:51]
	v_mfma_f32_16x16x32_bf16 v[36:39], v[160:163], v[202:205], v[36:39]
	v_mfma_f32_16x16x32_bf16 v[32:35], v[168:171], v[202:205], v[32:35]
	v_mfma_f32_16x16x32_bf16 v[20:23], v[160:163], v[210:213], v[20:23]
	v_mfma_f32_16x16x32_bf16 v[16:19], v[168:171], v[210:213], v[16:19]
	v_mfma_f32_16x16x32_bf16 v[8:11], v[160:163], v[218:221], v[8:11]
	v_mfma_f32_16x16x32_bf16 v[0:3], v[168:171], v[218:221], v[0:3]
	v_mfma_f32_16x16x32_bf16 v[60:63], v[172:175], v[190:193], v[60:63]
	v_mfma_f32_16x16x32_bf16 v[56:59], v[180:183], v[190:193], v[56:59]
	v_mfma_f32_16x16x32_bf16 v[44:47], v[172:175], v[198:201], v[44:47]
	v_mfma_f32_16x16x32_bf16 v[40:43], v[180:183], v[198:201], v[40:43]
	v_mfma_f32_16x16x32_bf16 v[28:31], v[172:175], v[206:209], v[28:31]
	v_mfma_f32_16x16x32_bf16 v[24:27], v[180:183], v[206:209], v[24:27]
	v_mfma_f32_16x16x32_bf16 v[12:15], v[172:175], v[214:217], v[12:15]
	v_mfma_f32_16x16x32_bf16 v[4:7], v[180:183], v[214:217], v[4:7]
	v_mfma_f32_16x16x32_bf16 v[60:63], v[176:179], v[194:197], v[60:63]
	v_mfma_f32_16x16x32_bf16 v[56:59], v[184:187], v[194:197], v[56:59]
	v_mfma_f32_16x16x32_bf16 v[44:47], v[176:179], v[202:205], v[44:47]
	v_mfma_f32_16x16x32_bf16 v[40:43], v[184:187], v[202:205], v[40:43]
	v_mfma_f32_16x16x32_bf16 v[28:31], v[176:179], v[210:213], v[28:31]
	v_mfma_f32_16x16x32_bf16 v[24:27], v[184:187], v[210:213], v[24:27]
	v_mfma_f32_16x16x32_bf16 v[12:15], v[176:179], v[218:221], v[12:15]
	v_mfma_f32_16x16x32_bf16 v[4:7], v[184:187], v[218:221], v[4:7]
	s_barrier
	s_add_i32 s49, 0, 0x18000
	s_add_i32 s50, 0, 0x1c000
	v_add_u32_e32 v168, s49, v149
	v_add_u32_e32 v184, s50, v149
	s_setprio 2
	ds_read_b128 v[156:159], v168
	ds_read_b128 v[160:163], v168 offset:1024
	ds_read_b128 v[164:167], v168 offset:2048
	ds_read_b128 v[168:171], v168 offset:3072
	ds_read_b128 v[172:175], v184
	ds_read_b128 v[176:179], v184 offset:1024
	ds_read_b128 v[180:183], v184 offset:2048
	ds_read_b128 v[184:187], v184 offset:3072
	s_add_u32 s30, s30, 0x80000
	s_addc_u32 s31, s31, 0
	s_mov_b32 m0, s29
	v_lshl_add_u64 v[228:229], s[30:31], 0, v[128:129]
	ds_read_b128 v[190:193], v153 offset:32768
	ds_read_b128 v[194:197], v153 offset:33792
	ds_read_b128 v[198:201], v153 offset:34816
	ds_read_b128 v[202:205], v153 offset:35840
	ds_read_b128 v[206:209], v153 offset:36864
	ds_read_b128 v[210:213], v153 offset:37888
	ds_read_b128 v[214:217], v153 offset:38912
	ds_read_b128 v[218:221], v153 offset:39936
	s_setprio 0
	global_load_lds_dwordx4 v[228:229], off
	v_lshl_add_u64 v[228:229], s[30:31], 0, v[132:133]
	s_mov_b32 m0, s33
	s_nop 0
	global_load_lds_dwordx4 v[228:229], off
	s_waitcnt vmcnt(8)
	s_waitcnt lgkmcnt(0)
	s_barrier
	v_mfma_f32_16x16x32_bf16 v[116:119], v[156:159], v[190:193], v[116:119]
	v_mfma_f32_16x16x32_bf16 v[112:115], v[164:167], v[190:193], v[112:115]
	v_mfma_f32_16x16x32_bf16 v[100:103], v[156:159], v[198:201], v[100:103]
	v_mfma_f32_16x16x32_bf16 v[96:99], v[164:167], v[198:201], v[96:99]
	v_mfma_f32_16x16x32_bf16 v[84:87], v[156:159], v[206:209], v[84:87]
	v_mfma_f32_16x16x32_bf16 v[80:83], v[164:167], v[206:209], v[80:83]
	v_mfma_f32_16x16x32_bf16 v[68:71], v[156:159], v[214:217], v[68:71]
	v_mfma_f32_16x16x32_bf16 v[64:67], v[164:167], v[214:217], v[64:67]
	v_mfma_f32_16x16x32_bf16 v[116:119], v[160:163], v[194:197], v[116:119]
	v_mfma_f32_16x16x32_bf16 v[112:115], v[168:171], v[194:197], v[112:115]
	v_mfma_f32_16x16x32_bf16 v[100:103], v[160:163], v[202:205], v[100:103]
	v_mfma_f32_16x16x32_bf16 v[96:99], v[168:171], v[202:205], v[96:99]
	v_mfma_f32_16x16x32_bf16 v[84:87], v[160:163], v[210:213], v[84:87]
	v_mfma_f32_16x16x32_bf16 v[80:83], v[168:171], v[210:213], v[80:83]
	v_mfma_f32_16x16x32_bf16 v[68:71], v[160:163], v[218:221], v[68:71]
	v_mfma_f32_16x16x32_bf16 v[64:67], v[168:171], v[218:221], v[64:67]
	v_mfma_f32_16x16x32_bf16 v[124:127], v[172:175], v[190:193], v[124:127]
	v_mfma_f32_16x16x32_bf16 v[120:123], v[180:183], v[190:193], v[120:123]
	v_mfma_f32_16x16x32_bf16 v[108:111], v[172:175], v[198:201], v[108:111]
	v_mfma_f32_16x16x32_bf16 v[104:107], v[180:183], v[198:201], v[104:107]
	v_mfma_f32_16x16x32_bf16 v[92:95], v[172:175], v[206:209], v[92:95]
	v_mfma_f32_16x16x32_bf16 v[88:91], v[180:183], v[206:209], v[88:91]
	v_mfma_f32_16x16x32_bf16 v[76:79], v[172:175], v[214:217], v[76:79]
	v_mfma_f32_16x16x32_bf16 v[72:75], v[180:183], v[214:217], v[72:75]
	v_mfma_f32_16x16x32_bf16 v[124:127], v[176:179], v[194:197], v[124:127]
	v_mfma_f32_16x16x32_bf16 v[120:123], v[184:187], v[194:197], v[120:123]
	v_mfma_f32_16x16x32_bf16 v[108:111], v[176:179], v[202:205], v[108:111]
	v_mfma_f32_16x16x32_bf16 v[104:107], v[184:187], v[202:205], v[104:107]
	v_mfma_f32_16x16x32_bf16 v[92:95], v[176:179], v[210:213], v[92:95]
	v_mfma_f32_16x16x32_bf16 v[88:91], v[184:187], v[210:213], v[88:91]
	v_mfma_f32_16x16x32_bf16 v[76:79], v[176:179], v[218:221], v[76:79]
	v_mfma_f32_16x16x32_bf16 v[72:75], v[184:187], v[218:221], v[72:75]
	s_barrier
	s_add_i32 s30, s49, s26
	v_lshl_add_u64 v[146:147], v[146:147], 0, s[6:7]
	s_mov_b32 m0, s30
	s_setprio 2
	ds_read_b128 v[190:193], v153 offset:49152
	ds_read_b128 v[194:197], v153 offset:50176
	ds_read_b128 v[198:201], v153 offset:51200
	ds_read_b128 v[202:205], v153 offset:52224
	ds_read_b128 v[206:209], v153 offset:53248
	ds_read_b128 v[210:213], v153 offset:54272
	ds_read_b128 v[214:217], v153 offset:55296
	ds_read_b128 v[218:221], v153 offset:56320
	s_setprio 0
	global_load_lds_dwordx4 v[146:147], off
	s_add_i32 m0, s30, 0x2000
	s_add_u32 s22, s22, 0x80080
	v_lshl_add_u64 v[146:147], v[222:223], 0, s[6:7]
	s_addc_u32 s23, s23, 0
	s_add_i32 s30, s50, s26
	global_load_lds_dwordx4 v[146:147], off
	v_lshl_add_u64 v[146:147], s[22:23], 0, v[130:131]
	s_mov_b32 m0, s30
	s_nop 0
	global_load_lds_dwordx4 v[146:147], off
	v_lshl_add_u64 v[146:147], s[22:23], 0, v[134:135]
	s_add_i32 m0, s30, 0x2000
	s_nop 0
	global_load_lds_dwordx4 v[146:147], off
	v_lshl_add_u64 v[146:147], v[224:225], 0, s[6:7]
	s_mov_b32 m0, s37
	s_nop 0
	global_load_lds_dwordx4 v[146:147], off
	v_lshl_add_u64 v[146:147], v[226:227], 0, s[6:7]
	s_mov_b32 m0, s38
	s_nop 0
	global_load_lds_dwordx4 v[146:147], off
	s_waitcnt vmcnt(8)
	s_waitcnt lgkmcnt(0)
	s_barrier
	v_mfma_f32_16x16x32_bf16 v[52:55], v[156:159], v[190:193], v[52:55]
	v_mfma_f32_16x16x32_bf16 v[48:51], v[164:167], v[190:193], v[48:51]
	v_mfma_f32_16x16x32_bf16 v[36:39], v[156:159], v[198:201], v[36:39]
	v_mfma_f32_16x16x32_bf16 v[32:35], v[164:167], v[198:201], v[32:35]
	v_mfma_f32_16x16x32_bf16 v[20:23], v[156:159], v[206:209], v[20:23]
	v_mfma_f32_16x16x32_bf16 v[16:19], v[164:167], v[206:209], v[16:19]
	v_mfma_f32_16x16x32_bf16 v[8:11], v[156:159], v[214:217], v[8:11]
	v_mfma_f32_16x16x32_bf16 v[0:3], v[164:167], v[214:217], v[0:3]
	v_mfma_f32_16x16x32_bf16 v[52:55], v[160:163], v[194:197], v[52:55]
	v_mfma_f32_16x16x32_bf16 v[48:51], v[168:171], v[194:197], v[48:51]
	v_mfma_f32_16x16x32_bf16 v[36:39], v[160:163], v[202:205], v[36:39]
	v_mfma_f32_16x16x32_bf16 v[32:35], v[168:171], v[202:205], v[32:35]
	v_mfma_f32_16x16x32_bf16 v[20:23], v[160:163], v[210:213], v[20:23]
	v_mfma_f32_16x16x32_bf16 v[16:19], v[168:171], v[210:213], v[16:19]
	v_mfma_f32_16x16x32_bf16 v[8:11], v[160:163], v[218:221], v[8:11]
	v_mfma_f32_16x16x32_bf16 v[0:3], v[168:171], v[218:221], v[0:3]
	v_mfma_f32_16x16x32_bf16 v[60:63], v[172:175], v[190:193], v[60:63]
	v_mfma_f32_16x16x32_bf16 v[56:59], v[180:183], v[190:193], v[56:59]
	v_mfma_f32_16x16x32_bf16 v[44:47], v[172:175], v[198:201], v[44:47]
	v_mfma_f32_16x16x32_bf16 v[40:43], v[180:183], v[198:201], v[40:43]
	v_mfma_f32_16x16x32_bf16 v[28:31], v[172:175], v[206:209], v[28:31]
	v_mfma_f32_16x16x32_bf16 v[24:27], v[180:183], v[206:209], v[24:27]
	v_mfma_f32_16x16x32_bf16 v[12:15], v[172:175], v[214:217], v[12:15]
	v_mfma_f32_16x16x32_bf16 v[4:7], v[180:183], v[214:217], v[4:7]
	v_mfma_f32_16x16x32_bf16 v[60:63], v[176:179], v[194:197], v[60:63]
	v_mfma_f32_16x16x32_bf16 v[56:59], v[184:187], v[194:197], v[56:59]
	v_mfma_f32_16x16x32_bf16 v[44:47], v[176:179], v[202:205], v[44:47]
	v_mfma_f32_16x16x32_bf16 v[40:43], v[184:187], v[202:205], v[40:43]
	v_mfma_f32_16x16x32_bf16 v[28:31], v[176:179], v[210:213], v[28:31]
	v_mfma_f32_16x16x32_bf16 v[24:27], v[184:187], v[210:213], v[24:27]
	v_mfma_f32_16x16x32_bf16 v[12:15], v[176:179], v[218:221], v[12:15]
	v_mfma_f32_16x16x32_bf16 v[4:7], v[184:187], v[218:221], v[4:7]
	s_barrier
	s_add_i32 s48, s48, 2
	s_add_u32 s20, s20, 0x100
	s_addc_u32 s21, s21, 0
	s_add_u32 s46, s46, 0x100
	s_addc_u32 s47, s47, 0
	s_cmp_gt_u32 s48, 29
	s_cbranch_scc0 .LBB0_664
	s_and_b64 vcc, exec, s[8:9]
	s_cbranch_vccz .LBB0_667
	s_barrier

.LBB0_749:
	s_setprio 2
	ds_read_b128 v[128:131], v179
	ds_read_b128 v[132:135], v179 offset:1024
	ds_read_b128 v[136:139], v179 offset:2048
	ds_read_b128 v[140:143], v179 offset:3072
	ds_read_b128 v[160:163], v180
	ds_read_b128 v[164:167], v180 offset:1024
	ds_read_b128 v[168:171], v180 offset:2048
	ds_read_b128 v[172:175], v180 offset:3072
	s_add_u32 s20, s10, 0xffea0080
	s_addc_u32 s21, s11, -1
	s_cmpk_eq_i32 s48, 0x54
	s_cselect_b32 s23, s1, s21
	s_cselect_b32 s22, s0, s20
	s_cselect_b32 s21, s19, s47
	s_cselect_b32 s20, s18, s46
	v_lshl_add_u64 v[218:219], s[10:11], 0, v[152:153]
	s_add_i32 m0, s27, 0xc000
	ds_read_b128 v[184:187], v181
	ds_read_b128 v[190:193], v181 offset:1024
	ds_read_b128 v[194:197], v181 offset:2048
	ds_read_b128 v[198:201], v181 offset:3072
	ds_read_b128 v[202:205], v181 offset:4096
	ds_read_b128 v[206:209], v181 offset:5120
	ds_read_b128 v[210:213], v181 offset:6144
	ds_read_b128 v[214:217], v181 offset:7168
	s_setprio 0
	global_load_lds_dwordx4 v[218:219], off
	v_lshl_add_u64 v[218:219], s[10:11], 0, v[154:155]
	s_add_i32 m0, s27, 0xe000
	s_nop 0
	global_load_lds_dwordx4 v[218:219], off
	s_waitcnt vmcnt(8)
	s_waitcnt lgkmcnt(0)
	s_barrier
	v_mfma_f32_16x16x32_bf16 v[124:127], v[128:131], v[184:187], v[124:127]
	v_mfma_f32_16x16x32_bf16 v[120:123], v[136:139], v[184:187], v[120:123]
	v_mfma_f32_16x16x32_bf16 v[108:111], v[128:131], v[194:197], v[108:111]
	v_mfma_f32_16x16x32_bf16 v[104:107], v[136:139], v[194:197], v[104:107]
	v_mfma_f32_16x16x32_bf16 v[92:95], v[128:131], v[202:205], v[92:95]
	v_mfma_f32_16x16x32_bf16 v[88:91], v[136:139], v[202:205], v[88:91]
	v_mfma_f32_16x16x32_bf16 v[76:79], v[128:131], v[210:213], v[76:79]
	v_mfma_f32_16x16x32_bf16 v[72:75], v[136:139], v[210:213], v[72:75]
	v_mfma_f32_16x16x32_bf16 v[124:127], v[132:135], v[190:193], v[124:127]
	v_mfma_f32_16x16x32_bf16 v[120:123], v[140:143], v[190:193], v[120:123]
	v_mfma_f32_16x16x32_bf16 v[108:111], v[132:135], v[198:201], v[108:111]
	v_mfma_f32_16x16x32_bf16 v[104:107], v[140:143], v[198:201], v[104:107]
	v_mfma_f32_16x16x32_bf16 v[92:95], v[132:135], v[206:209], v[92:95]
	v_mfma_f32_16x16x32_bf16 v[88:91], v[140:143], v[206:209], v[88:91]
	v_mfma_f32_16x16x32_bf16 v[76:79], v[132:135], v[214:217], v[76:79]
	v_mfma_f32_16x16x32_bf16 v[72:75], v[140:143], v[214:217], v[72:75]
	v_mfma_f32_16x16x32_bf16 v[116:119], v[160:163], v[184:187], v[116:119]
	v_mfma_f32_16x16x32_bf16 v[112:115], v[168:171], v[184:187], v[112:115]
	v_mfma_f32_16x16x32_bf16 v[100:103], v[160:163], v[194:197], v[100:103]
	v_mfma_f32_16x16x32_bf16 v[96:99], v[168:171], v[194:197], v[96:99]
	v_mfma_f32_16x16x32_bf16 v[84:87], v[160:163], v[202:205], v[84:87]
	v_mfma_f32_16x16x32_bf16 v[80:83], v[168:171], v[202:205], v[80:83]
	v_mfma_f32_16x16x32_bf16 v[68:71], v[160:163], v[210:213], v[68:71]
	v_mfma_f32_16x16x32_bf16 v[64:67], v[168:171], v[210:213], v[64:67]
	v_mfma_f32_16x16x32_bf16 v[116:119], v[164:167], v[190:193], v[116:119]
	v_mfma_f32_16x16x32_bf16 v[112:115], v[172:175], v[190:193], v[112:115]
	v_mfma_f32_16x16x32_bf16 v[100:103], v[164:167], v[198:201], v[100:103]
	v_mfma_f32_16x16x32_bf16 v[96:99], v[172:175], v[198:201], v[96:99]
	v_mfma_f32_16x16x32_bf16 v[84:87], v[164:167], v[206:209], v[84:87]
	v_mfma_f32_16x16x32_bf16 v[80:83], v[172:175], v[206:209], v[80:83]
	v_mfma_f32_16x16x32_bf16 v[68:71], v[164:167], v[214:217], v[68:71]
	v_mfma_f32_16x16x32_bf16 v[64:67], v[172:175], v[214:217], v[64:67]
	s_barrier
	s_add_i32 s49, s39, s26
	v_lshl_add_u64 v[218:219], s[20:21], 0, v[146:147]
	s_mov_b32 m0, s49
	s_setprio 2
	ds_read_b128 v[184:187], v181 offset:16384
	ds_read_b128 v[190:193], v181 offset:17408
	ds_read_b128 v[194:197], v181 offset:18432
	ds_read_b128 v[198:201], v181 offset:19456
	ds_read_b128 v[202:205], v181 offset:20480
	ds_read_b128 v[206:209], v181 offset:21504
	ds_read_b128 v[210:213], v181 offset:22528
	ds_read_b128 v[214:217], v181 offset:23552
	s_setprio 0
	global_load_lds_dwordx4 v[218:219], off
	s_add_i32 m0, s49, 0x2000
	s_add_u32 s50, s20, 0x160000
	v_lshl_add_u64 v[220:221], s[20:21], 0, v[150:151]
	s_addc_u32 s51, s21, 0
	s_add_i32 s49, s40, s26
	global_load_lds_dwordx4 v[220:221], off
	v_lshl_add_u64 v[222:223], s[50:51], 0, v[146:147]
	s_mov_b32 m0, s49
	v_lshl_add_u64 v[224:225], s[22:23], 0, v[148:149]
	global_load_lds_dwordx4 v[222:223], off
	v_lshl_add_u64 v[222:223], s[50:51], 0, v[150:151]
	s_add_i32 m0, s49, 0x2000
	s_nop 0
	global_load_lds_dwordx4 v[222:223], off
	v_lshl_add_u64 v[222:223], s[22:23], 0, v[144:145]
	s_mov_b32 m0, s27
	s_nop 0
	global_load_lds_dwordx4 v[222:223], off
	s_mov_b32 m0, s28
	s_nop 0
	global_load_lds_dwordx4 v[224:225], off
	s_waitcnt vmcnt(8)
	s_waitcnt lgkmcnt(0)
	s_barrier
	v_mfma_f32_16x16x32_bf16 v[60:63], v[128:131], v[184:187], v[60:63]
	v_mfma_f32_16x16x32_bf16 v[56:59], v[136:139], v[184:187], v[56:59]
	v_mfma_f32_16x16x32_bf16 v[44:47], v[128:131], v[194:197], v[44:47]
	v_mfma_f32_16x16x32_bf16 v[40:43], v[136:139], v[194:197], v[40:43]
	v_mfma_f32_16x16x32_bf16 v[28:31], v[128:131], v[202:205], v[28:31]
	v_mfma_f32_16x16x32_bf16 v[24:27], v[136:139], v[202:205], v[24:27]
	v_mfma_f32_16x16x32_bf16 v[12:15], v[128:131], v[210:213], v[12:15]
	v_mfma_f32_16x16x32_bf16 v[8:11], v[136:139], v[210:213], v[8:11]
	v_mfma_f32_16x16x32_bf16 v[60:63], v[132:135], v[190:193], v[60:63]
	v_mfma_f32_16x16x32_bf16 v[56:59], v[140:143], v[190:193], v[56:59]
	v_mfma_f32_16x16x32_bf16 v[44:47], v[132:135], v[198:201], v[44:47]
	v_mfma_f32_16x16x32_bf16 v[40:43], v[140:143], v[198:201], v[40:43]
	v_mfma_f32_16x16x32_bf16 v[28:31], v[132:135], v[206:209], v[28:31]
	v_mfma_f32_16x16x32_bf16 v[24:27], v[140:143], v[206:209], v[24:27]
	v_mfma_f32_16x16x32_bf16 v[12:15], v[132:135], v[214:217], v[12:15]
	v_mfma_f32_16x16x32_bf16 v[8:11], v[140:143], v[214:217], v[8:11]
	v_mfma_f32_16x16x32_bf16 v[52:55], v[160:163], v[184:187], v[52:55]
	v_mfma_f32_16x16x32_bf16 v[48:51], v[168:171], v[184:187], v[48:51]
	v_mfma_f32_16x16x32_bf16 v[36:39], v[160:163], v[194:197], v[36:39]
	v_mfma_f32_16x16x32_bf16 v[32:35], v[168:171], v[194:197], v[32:35]
	v_mfma_f32_16x16x32_bf16 v[20:23], v[160:163], v[202:205], v[20:23]
	v_mfma_f32_16x16x32_bf16 v[16:19], v[168:171], v[202:205], v[16:19]
	v_mfma_f32_16x16x32_bf16 v[4:7], v[160:163], v[210:213], v[4:7]
	v_mfma_f32_16x16x32_bf16 v[0:3], v[168:171], v[210:213], v[0:3]
	v_mfma_f32_16x16x32_bf16 v[52:55], v[164:167], v[190:193], v[52:55]
	v_mfma_f32_16x16x32_bf16 v[48:51], v[172:175], v[190:193], v[48:51]
	v_mfma_f32_16x16x32_bf16 v[36:39], v[164:167], v[198:201], v[36:39]
	v_mfma_f32_16x16x32_bf16 v[32:35], v[172:175], v[198:201], v[32:35]
	v_mfma_f32_16x16x32_bf16 v[20:23], v[164:167], v[206:209], v[20:23]
	v_mfma_f32_16x16x32_bf16 v[16:19], v[172:175], v[206:209], v[16:19]
	v_mfma_f32_16x16x32_bf16 v[4:7], v[164:167], v[214:217], v[4:7]
	v_mfma_f32_16x16x32_bf16 v[0:3], v[172:175], v[214:217], v[0:3]
	s_barrier
	s_add_i32 s49, 0, 0x18000
	s_add_i32 s50, 0, 0x1c000
	v_add_u32_e32 v140, s49, v177
	v_add_u32_e32 v172, s50, v177
	s_setprio 2
	ds_read_b128 v[128:131], v140
	ds_read_b128 v[132:135], v140 offset:1024
	ds_read_b128 v[136:139], v140 offset:2048
	ds_read_b128 v[140:143], v140 offset:3072
	ds_read_b128 v[160:163], v172
	ds_read_b128 v[164:167], v172 offset:1024
	ds_read_b128 v[168:171], v172 offset:2048
	ds_read_b128 v[172:175], v172 offset:3072
	s_add_u32 s22, s22, 0x160000
	s_addc_u32 s23, s23, 0
	s_mov_b32 m0, s29
	v_lshl_add_u64 v[226:227], s[22:23], 0, v[144:145]
	ds_read_b128 v[184:187], v181 offset:32768
	ds_read_b128 v[190:193], v181 offset:33792
	ds_read_b128 v[194:197], v181 offset:34816
	ds_read_b128 v[198:201], v181 offset:35840
	ds_read_b128 v[202:205], v181 offset:36864
	ds_read_b128 v[206:209], v181 offset:37888
	ds_read_b128 v[210:213], v181 offset:38912
	ds_read_b128 v[214:217], v181 offset:39936
	s_setprio 0
	global_load_lds_dwordx4 v[226:227], off
	v_lshl_add_u64 v[226:227], s[22:23], 0, v[148:149]
	s_mov_b32 m0, s30
	s_nop 0
	global_load_lds_dwordx4 v[226:227], off
	s_waitcnt vmcnt(8)
	s_waitcnt lgkmcnt(0)
	s_barrier
	v_mfma_f32_16x16x32_bf16 v[124:127], v[128:131], v[184:187], v[124:127]
	v_mfma_f32_16x16x32_bf16 v[120:123], v[136:139], v[184:187], v[120:123]
	v_mfma_f32_16x16x32_bf16 v[108:111], v[128:131], v[194:197], v[108:111]
	v_mfma_f32_16x16x32_bf16 v[104:107], v[136:139], v[194:197], v[104:107]
	v_mfma_f32_16x16x32_bf16 v[92:95], v[128:131], v[202:205], v[92:95]
	v_mfma_f32_16x16x32_bf16 v[88:91], v[136:139], v[202:205], v[88:91]
	v_mfma_f32_16x16x32_bf16 v[76:79], v[128:131], v[210:213], v[76:79]
	v_mfma_f32_16x16x32_bf16 v[72:75], v[136:139], v[210:213], v[72:75]
	v_mfma_f32_16x16x32_bf16 v[124:127], v[132:135], v[190:193], v[124:127]
	v_mfma_f32_16x16x32_bf16 v[120:123], v[140:143], v[190:193], v[120:123]
	v_mfma_f32_16x16x32_bf16 v[108:111], v[132:135], v[198:201], v[108:111]
	v_mfma_f32_16x16x32_bf16 v[104:107], v[140:143], v[198:201], v[104:107]
	v_mfma_f32_16x16x32_bf16 v[92:95], v[132:135], v[206:209], v[92:95]
	v_mfma_f32_16x16x32_bf16 v[88:91], v[140:143], v[206:209], v[88:91]
	v_mfma_f32_16x16x32_bf16 v[76:79], v[132:135], v[214:217], v[76:79]
	v_mfma_f32_16x16x32_bf16 v[72:75], v[140:143], v[214:217], v[72:75]
	v_mfma_f32_16x16x32_bf16 v[116:119], v[160:163], v[184:187], v[116:119]
	v_mfma_f32_16x16x32_bf16 v[112:115], v[168:171], v[184:187], v[112:115]
	v_mfma_f32_16x16x32_bf16 v[100:103], v[160:163], v[194:197], v[100:103]
	v_mfma_f32_16x16x32_bf16 v[96:99], v[168:171], v[194:197], v[96:99]
	v_mfma_f32_16x16x32_bf16 v[84:87], v[160:163], v[202:205], v[84:87]
	v_mfma_f32_16x16x32_bf16 v[80:83], v[168:171], v[202:205], v[80:83]
	v_mfma_f32_16x16x32_bf16 v[68:71], v[160:163], v[210:213], v[68:71]
	v_mfma_f32_16x16x32_bf16 v[64:67], v[168:171], v[210:213], v[64:67]
	v_mfma_f32_16x16x32_bf16 v[116:119], v[164:167], v[190:193], v[116:119]
	v_mfma_f32_16x16x32_bf16 v[112:115], v[172:175], v[190:193], v[112:115]
	v_mfma_f32_16x16x32_bf16 v[100:103], v[164:167], v[198:201], v[100:103]
	v_mfma_f32_16x16x32_bf16 v[96:99], v[172:175], v[198:201], v[96:99]
	v_mfma_f32_16x16x32_bf16 v[84:87], v[164:167], v[206:209], v[84:87]
	v_mfma_f32_16x16x32_bf16 v[80:83], v[172:175], v[206:209], v[80:83]
	v_mfma_f32_16x16x32_bf16 v[68:71], v[164:167], v[214:217], v[68:71]
	v_mfma_f32_16x16x32_bf16 v[64:67], v[172:175], v[214:217], v[64:67]
	s_barrier
	s_add_i32 s22, s49, s26
	v_lshl_add_u64 v[218:219], v[218:219], 0, s[12:13]
	s_mov_b32 m0, s22
	s_setprio 2
	ds_read_b128 v[184:187], v181 offset:49152
	ds_read_b128 v[190:193], v181 offset:50176
	ds_read_b128 v[194:197], v181 offset:51200
	ds_read_b128 v[198:201], v181 offset:52224
	ds_read_b128 v[202:205], v181 offset:53248
	ds_read_b128 v[206:209], v181 offset:54272
	ds_read_b128 v[210:213], v181 offset:55296
	ds_read_b128 v[214:217], v181 offset:56320
	s_setprio 0
	global_load_lds_dwordx4 v[218:219], off
	s_add_i32 m0, s22, 0x2000
	s_add_u32 s20, s20, 0x160080
	v_lshl_add_u64 v[218:219], v[220:221], 0, s[12:13]
	s_addc_u32 s21, s21, 0
	s_add_i32 s22, s50, s26
	global_load_lds_dwordx4 v[218:219], off
	v_lshl_add_u64 v[218:219], s[20:21], 0, v[146:147]
	s_mov_b32 m0, s22
	s_nop 0
	global_load_lds_dwordx4 v[218:219], off
	v_lshl_add_u64 v[218:219], s[20:21], 0, v[150:151]
	s_add_i32 m0, s22, 0x2000
	s_nop 0
	global_load_lds_dwordx4 v[218:219], off
	v_lshl_add_u64 v[218:219], v[222:223], 0, s[12:13]
	s_mov_b32 m0, s35
	s_nop 0
	global_load_lds_dwordx4 v[218:219], off
	v_lshl_add_u64 v[218:219], v[224:225], 0, s[12:13]
	s_mov_b32 m0, s36
	s_nop 0
	global_load_lds_dwordx4 v[218:219], off
	s_waitcnt vmcnt(8)
	s_waitcnt lgkmcnt(0)
	s_barrier
	v_mfma_f32_16x16x32_bf16 v[60:63], v[128:131], v[184:187], v[60:63]
	v_mfma_f32_16x16x32_bf16 v[56:59], v[136:139], v[184:187], v[56:59]
	v_mfma_f32_16x16x32_bf16 v[44:47], v[128:131], v[194:197], v[44:47]
	v_mfma_f32_16x16x32_bf16 v[40:43], v[136:139], v[194:197], v[40:43]
	v_mfma_f32_16x16x32_bf16 v[28:31], v[128:131], v[202:205], v[28:31]
	v_mfma_f32_16x16x32_bf16 v[24:27], v[136:139], v[202:205], v[24:27]
	v_mfma_f32_16x16x32_bf16 v[12:15], v[128:131], v[210:213], v[12:15]
	v_mfma_f32_16x16x32_bf16 v[8:11], v[136:139], v[210:213], v[8:11]
	v_mfma_f32_16x16x32_bf16 v[60:63], v[132:135], v[190:193], v[60:63]
	v_mfma_f32_16x16x32_bf16 v[56:59], v[140:143], v[190:193], v[56:59]
	v_mfma_f32_16x16x32_bf16 v[44:47], v[132:135], v[198:201], v[44:47]
	v_mfma_f32_16x16x32_bf16 v[40:43], v[140:143], v[198:201], v[40:43]
	v_mfma_f32_16x16x32_bf16 v[28:31], v[132:135], v[206:209], v[28:31]
	v_mfma_f32_16x16x32_bf16 v[24:27], v[140:143], v[206:209], v[24:27]
	v_mfma_f32_16x16x32_bf16 v[12:15], v[132:135], v[214:217], v[12:15]
	v_mfma_f32_16x16x32_bf16 v[8:11], v[140:143], v[214:217], v[8:11]
	v_mfma_f32_16x16x32_bf16 v[52:55], v[160:163], v[184:187], v[52:55]
	v_mfma_f32_16x16x32_bf16 v[48:51], v[168:171], v[184:187], v[48:51]
	v_mfma_f32_16x16x32_bf16 v[36:39], v[160:163], v[194:197], v[36:39]
	v_mfma_f32_16x16x32_bf16 v[32:35], v[168:171], v[194:197], v[32:35]
	v_mfma_f32_16x16x32_bf16 v[20:23], v[160:163], v[202:205], v[20:23]
	v_mfma_f32_16x16x32_bf16 v[16:19], v[168:171], v[202:205], v[16:19]
	v_mfma_f32_16x16x32_bf16 v[4:7], v[160:163], v[210:213], v[4:7]
	v_mfma_f32_16x16x32_bf16 v[0:3], v[168:171], v[210:213], v[0:3]
	v_mfma_f32_16x16x32_bf16 v[52:55], v[164:167], v[190:193], v[52:55]
	v_mfma_f32_16x16x32_bf16 v[48:51], v[172:175], v[190:193], v[48:51]
	v_mfma_f32_16x16x32_bf16 v[36:39], v[164:167], v[198:201], v[36:39]
	v_mfma_f32_16x16x32_bf16 v[32:35], v[172:175], v[198:201], v[32:35]
	v_mfma_f32_16x16x32_bf16 v[20:23], v[164:167], v[206:209], v[20:23]
	v_mfma_f32_16x16x32_bf16 v[16:19], v[172:175], v[206:209], v[16:19]
	v_mfma_f32_16x16x32_bf16 v[4:7], v[164:167], v[214:217], v[4:7]
	v_mfma_f32_16x16x32_bf16 v[0:3], v[172:175], v[214:217], v[0:3]
	s_barrier
	s_add_i32 s48, s48, 2
	s_add_u32 s10, s10, 0x100
	s_addc_u32 s11, s11, 0
	s_add_u32 s46, s46, 0x100
	s_addc_u32 s47, s47, 0
	s_cmpk_gt_u32 s48, 0x55
	s_cbranch_scc0 .LBB0_749
	s_and_b64 vcc, exec, s[14:15]
	s_cbranch_vccz .LBB0_752
	s_barrier

.LBB0_838:
	s_setprio 2
	ds_read_b128 v[154:157], v143
	ds_read_b128 v[164:167], v143 offset:1024
	ds_read_b128 v[168:171], v143 offset:2048
	ds_read_b128 v[172:175], v143 offset:3072
	ds_read_b128 v[176:179], v160
	ds_read_b128 v[180:183], v160 offset:1024
	ds_read_b128 v[184:187], v160 offset:2048
	ds_read_b128 v[190:193], v160 offset:3072
	s_add_u32 s44, s10, 0xfff80080
	s_addc_u32 s45, s11, -1
	s_cmp_eq_u32 s62, 28
	s_cselect_b32 s47, s7, s45
	s_cselect_b32 s46, s35, s44
	s_cselect_b32 s45, s37, s61
	s_cselect_b32 s44, s59, s60
	v_lshl_add_u64 v[226:227], s[10:11], 0, v[146:147]
	s_add_i32 m0, s27, 0xc000
	ds_read_b128 v[194:197], v161
	ds_read_b128 v[198:201], v161 offset:1024
	ds_read_b128 v[202:205], v161 offset:2048
	ds_read_b128 v[206:209], v161 offset:3072
	ds_read_b128 v[210:213], v161 offset:4096
	ds_read_b128 v[214:217], v161 offset:5120
	ds_read_b128 v[218:221], v161 offset:6144
	ds_read_b128 v[222:225], v161 offset:7168
	s_setprio 0
	global_load_lds_dwordx4 v[226:227], off
	v_lshl_add_u64 v[226:227], s[10:11], 0, v[148:149]
	s_add_i32 m0, s27, 0xe000
	s_nop 0
	global_load_lds_dwordx4 v[226:227], off
	s_waitcnt vmcnt(8)
	s_waitcnt lgkmcnt(0)
	s_barrier
	v_mfma_f32_16x16x32_bf16 v[124:127], v[154:157], v[194:197], v[124:127]
	v_mfma_f32_16x16x32_bf16 v[120:123], v[168:171], v[194:197], v[120:123]
	v_mfma_f32_16x16x32_bf16 v[108:111], v[154:157], v[202:205], v[108:111]
	v_mfma_f32_16x16x32_bf16 v[104:107], v[168:171], v[202:205], v[104:107]
	v_mfma_f32_16x16x32_bf16 v[92:95], v[154:157], v[210:213], v[92:95]
	v_mfma_f32_16x16x32_bf16 v[88:91], v[168:171], v[210:213], v[88:91]
	v_mfma_f32_16x16x32_bf16 v[76:79], v[154:157], v[218:221], v[76:79]
	v_mfma_f32_16x16x32_bf16 v[72:75], v[168:171], v[218:221], v[72:75]
	v_mfma_f32_16x16x32_bf16 v[124:127], v[164:167], v[198:201], v[124:127]
	v_mfma_f32_16x16x32_bf16 v[120:123], v[172:175], v[198:201], v[120:123]
	v_mfma_f32_16x16x32_bf16 v[108:111], v[164:167], v[206:209], v[108:111]
	v_mfma_f32_16x16x32_bf16 v[104:107], v[172:175], v[206:209], v[104:107]
	v_mfma_f32_16x16x32_bf16 v[92:95], v[164:167], v[214:217], v[92:95]
	v_mfma_f32_16x16x32_bf16 v[88:91], v[172:175], v[214:217], v[88:91]
	v_mfma_f32_16x16x32_bf16 v[76:79], v[164:167], v[222:225], v[76:79]
	v_mfma_f32_16x16x32_bf16 v[72:75], v[172:175], v[222:225], v[72:75]
	v_mfma_f32_16x16x32_bf16 v[116:119], v[176:179], v[194:197], v[116:119]
	v_mfma_f32_16x16x32_bf16 v[112:115], v[184:187], v[194:197], v[112:115]
	v_mfma_f32_16x16x32_bf16 v[100:103], v[176:179], v[202:205], v[100:103]
	v_mfma_f32_16x16x32_bf16 v[96:99], v[184:187], v[202:205], v[96:99]
	v_mfma_f32_16x16x32_bf16 v[84:87], v[176:179], v[210:213], v[84:87]
	v_mfma_f32_16x16x32_bf16 v[80:83], v[184:187], v[210:213], v[80:83]
	v_mfma_f32_16x16x32_bf16 v[68:71], v[176:179], v[218:221], v[68:71]
	v_mfma_f32_16x16x32_bf16 v[64:67], v[184:187], v[218:221], v[64:67]
	v_mfma_f32_16x16x32_bf16 v[116:119], v[180:183], v[198:201], v[116:119]
	v_mfma_f32_16x16x32_bf16 v[112:115], v[190:193], v[198:201], v[112:115]
	v_mfma_f32_16x16x32_bf16 v[100:103], v[180:183], v[206:209], v[100:103]
	v_mfma_f32_16x16x32_bf16 v[96:99], v[190:193], v[206:209], v[96:99]
	v_mfma_f32_16x16x32_bf16 v[84:87], v[180:183], v[214:217], v[84:87]
	v_mfma_f32_16x16x32_bf16 v[80:83], v[190:193], v[214:217], v[80:83]
	v_mfma_f32_16x16x32_bf16 v[68:71], v[180:183], v[222:225], v[68:71]
	v_mfma_f32_16x16x32_bf16 v[64:67], v[190:193], v[222:225], v[64:67]
	s_barrier
	s_add_i32 s63, s54, s26
	v_lshl_add_u64 v[226:227], s[44:45], 0, v[130:131]
	s_mov_b32 m0, s63
	s_setprio 2
	ds_read_b128 v[194:197], v161 offset:16384
	ds_read_b128 v[198:201], v161 offset:17408
	ds_read_b128 v[202:205], v161 offset:18432
	ds_read_b128 v[206:209], v161 offset:19456
	ds_read_b128 v[210:213], v161 offset:20480
	ds_read_b128 v[214:217], v161 offset:21504
	ds_read_b128 v[218:221], v161 offset:22528
	ds_read_b128 v[222:225], v161 offset:23552
	s_setprio 0
	global_load_lds_dwordx4 v[226:227], off
	s_add_i32 m0, s63, 0x2000
	s_add_u32 s64, s44, 0x80000
	v_lshl_add_u64 v[228:229], s[44:45], 0, v[134:135]
	s_addc_u32 s65, s45, 0
	s_add_i32 s63, s55, s26
	global_load_lds_dwordx4 v[228:229], off
	v_lshl_add_u64 v[230:231], s[64:65], 0, v[130:131]
	s_mov_b32 m0, s63
	v_lshl_add_u64 v[232:233], s[46:47], 0, v[132:133]
	global_load_lds_dwordx4 v[230:231], off
	v_lshl_add_u64 v[230:231], s[64:65], 0, v[134:135]
	s_add_i32 m0, s63, 0x2000
	s_nop 0
	global_load_lds_dwordx4 v[230:231], off
	v_lshl_add_u64 v[230:231], s[46:47], 0, v[128:129]
	s_mov_b32 m0, s27
	s_nop 0
	global_load_lds_dwordx4 v[230:231], off
	s_mov_b32 m0, s28
	s_nop 0
	global_load_lds_dwordx4 v[232:233], off
	s_waitcnt vmcnt(8)
	s_waitcnt lgkmcnt(0)
	s_barrier
	v_mfma_f32_16x16x32_bf16 v[60:63], v[154:157], v[194:197], v[60:63]
	v_mfma_f32_16x16x32_bf16 v[56:59], v[168:171], v[194:197], v[56:59]
	v_mfma_f32_16x16x32_bf16 v[44:47], v[154:157], v[202:205], v[44:47]
	v_mfma_f32_16x16x32_bf16 v[40:43], v[168:171], v[202:205], v[40:43]
	v_mfma_f32_16x16x32_bf16 v[28:31], v[154:157], v[210:213], v[28:31]
	v_mfma_f32_16x16x32_bf16 v[24:27], v[168:171], v[210:213], v[24:27]
	v_mfma_f32_16x16x32_bf16 v[12:15], v[154:157], v[218:221], v[12:15]
	v_mfma_f32_16x16x32_bf16 v[8:11], v[168:171], v[218:221], v[8:11]
	v_mfma_f32_16x16x32_bf16 v[60:63], v[164:167], v[198:201], v[60:63]
	v_mfma_f32_16x16x32_bf16 v[56:59], v[172:175], v[198:201], v[56:59]
	v_mfma_f32_16x16x32_bf16 v[44:47], v[164:167], v[206:209], v[44:47]
	v_mfma_f32_16x16x32_bf16 v[40:43], v[172:175], v[206:209], v[40:43]
	v_mfma_f32_16x16x32_bf16 v[28:31], v[164:167], v[214:217], v[28:31]
	v_mfma_f32_16x16x32_bf16 v[24:27], v[172:175], v[214:217], v[24:27]
	v_mfma_f32_16x16x32_bf16 v[12:15], v[164:167], v[222:225], v[12:15]
	v_mfma_f32_16x16x32_bf16 v[8:11], v[172:175], v[222:225], v[8:11]
	v_mfma_f32_16x16x32_bf16 v[52:55], v[176:179], v[194:197], v[52:55]
	v_mfma_f32_16x16x32_bf16 v[48:51], v[184:187], v[194:197], v[48:51]
	v_mfma_f32_16x16x32_bf16 v[36:39], v[176:179], v[202:205], v[36:39]
	v_mfma_f32_16x16x32_bf16 v[32:35], v[184:187], v[202:205], v[32:35]
	v_mfma_f32_16x16x32_bf16 v[20:23], v[176:179], v[210:213], v[20:23]
	v_mfma_f32_16x16x32_bf16 v[16:19], v[184:187], v[210:213], v[16:19]
	v_mfma_f32_16x16x32_bf16 v[4:7], v[176:179], v[218:221], v[4:7]
	v_mfma_f32_16x16x32_bf16 v[0:3], v[184:187], v[218:221], v[0:3]
	v_mfma_f32_16x16x32_bf16 v[52:55], v[180:183], v[198:201], v[52:55]
	v_mfma_f32_16x16x32_bf16 v[48:51], v[190:193], v[198:201], v[48:51]
	v_mfma_f32_16x16x32_bf16 v[36:39], v[180:183], v[206:209], v[36:39]
	v_mfma_f32_16x16x32_bf16 v[32:35], v[190:193], v[206:209], v[32:35]
	v_mfma_f32_16x16x32_bf16 v[20:23], v[180:183], v[214:217], v[20:23]
	v_mfma_f32_16x16x32_bf16 v[16:19], v[190:193], v[214:217], v[16:19]
	v_mfma_f32_16x16x32_bf16 v[4:7], v[180:183], v[222:225], v[4:7]
	v_mfma_f32_16x16x32_bf16 v[0:3], v[190:193], v[222:225], v[0:3]
	s_barrier
	s_add_i32 s63, 0, 0x18000
	v_add_u32_e32 v136, s63, v159
	s_add_i32 s64, 0, 0x1c000
	s_setprio 2
	ds_read_b128 v[154:157], v136
	ds_read_b128 v[164:167], v136 offset:1024
	ds_read_b128 v[168:171], v136 offset:2048
	ds_read_b128 v[172:175], v136 offset:3072
	v_add_u32_e32 v136, s64, v159
	ds_read_b128 v[176:179], v136
	ds_read_b128 v[180:183], v136 offset:1024
	ds_read_b128 v[184:187], v136 offset:2048
	ds_read_b128 v[190:193], v136 offset:3072
	s_add_u32 s46, s46, 0x80000
	s_addc_u32 s47, s47, 0
	s_mov_b32 m0, s29
	v_lshl_add_u64 v[234:235], s[46:47], 0, v[128:129]
	ds_read_b128 v[194:197], v161 offset:32768
	ds_read_b128 v[198:201], v161 offset:33792
	ds_read_b128 v[202:205], v161 offset:34816
	ds_read_b128 v[206:209], v161 offset:35840
	ds_read_b128 v[210:213], v161 offset:36864
	ds_read_b128 v[214:217], v161 offset:37888
	ds_read_b128 v[218:221], v161 offset:38912
	ds_read_b128 v[222:225], v161 offset:39936
	s_setprio 0
	global_load_lds_dwordx4 v[234:235], off
	v_lshl_add_u64 v[234:235], s[46:47], 0, v[132:133]
	s_mov_b32 m0, s33
	s_nop 0
	global_load_lds_dwordx4 v[234:235], off
	s_waitcnt vmcnt(8)
	s_waitcnt lgkmcnt(0)
	s_barrier
	v_mfma_f32_16x16x32_bf16 v[124:127], v[154:157], v[194:197], v[124:127]
	v_mfma_f32_16x16x32_bf16 v[120:123], v[168:171], v[194:197], v[120:123]
	v_mfma_f32_16x16x32_bf16 v[108:111], v[154:157], v[202:205], v[108:111]
	v_mfma_f32_16x16x32_bf16 v[104:107], v[168:171], v[202:205], v[104:107]
	v_mfma_f32_16x16x32_bf16 v[92:95], v[154:157], v[210:213], v[92:95]
	v_mfma_f32_16x16x32_bf16 v[88:91], v[168:171], v[210:213], v[88:91]
	v_mfma_f32_16x16x32_bf16 v[76:79], v[154:157], v[218:221], v[76:79]
	v_mfma_f32_16x16x32_bf16 v[72:75], v[168:171], v[218:221], v[72:75]
	v_mfma_f32_16x16x32_bf16 v[124:127], v[164:167], v[198:201], v[124:127]
	v_mfma_f32_16x16x32_bf16 v[120:123], v[172:175], v[198:201], v[120:123]
	v_mfma_f32_16x16x32_bf16 v[108:111], v[164:167], v[206:209], v[108:111]
	v_mfma_f32_16x16x32_bf16 v[104:107], v[172:175], v[206:209], v[104:107]
	v_mfma_f32_16x16x32_bf16 v[92:95], v[164:167], v[214:217], v[92:95]
	v_mfma_f32_16x16x32_bf16 v[88:91], v[172:175], v[214:217], v[88:91]
	v_mfma_f32_16x16x32_bf16 v[76:79], v[164:167], v[222:225], v[76:79]
	v_mfma_f32_16x16x32_bf16 v[72:75], v[172:175], v[222:225], v[72:75]
	v_mfma_f32_16x16x32_bf16 v[116:119], v[176:179], v[194:197], v[116:119]
	v_mfma_f32_16x16x32_bf16 v[112:115], v[184:187], v[194:197], v[112:115]
	v_mfma_f32_16x16x32_bf16 v[100:103], v[176:179], v[202:205], v[100:103]
	v_mfma_f32_16x16x32_bf16 v[96:99], v[184:187], v[202:205], v[96:99]
	v_mfma_f32_16x16x32_bf16 v[84:87], v[176:179], v[210:213], v[84:87]
	v_mfma_f32_16x16x32_bf16 v[80:83], v[184:187], v[210:213], v[80:83]
	v_mfma_f32_16x16x32_bf16 v[68:71], v[176:179], v[218:221], v[68:71]
	v_mfma_f32_16x16x32_bf16 v[64:67], v[184:187], v[218:221], v[64:67]
	v_mfma_f32_16x16x32_bf16 v[116:119], v[180:183], v[198:201], v[116:119]
	v_mfma_f32_16x16x32_bf16 v[112:115], v[190:193], v[198:201], v[112:115]
	v_mfma_f32_16x16x32_bf16 v[100:103], v[180:183], v[206:209], v[100:103]
	v_mfma_f32_16x16x32_bf16 v[96:99], v[190:193], v[206:209], v[96:99]
	v_mfma_f32_16x16x32_bf16 v[84:87], v[180:183], v[214:217], v[84:87]
	v_mfma_f32_16x16x32_bf16 v[80:83], v[190:193], v[214:217], v[80:83]
	v_mfma_f32_16x16x32_bf16 v[68:71], v[180:183], v[222:225], v[68:71]
	v_mfma_f32_16x16x32_bf16 v[64:67], v[190:193], v[222:225], v[64:67]
	s_barrier
	s_add_i32 s46, s63, s26
	v_lshl_add_u64 v[226:227], v[226:227], 0, s[18:19]
	s_mov_b32 m0, s46
	s_setprio 2
	ds_read_b128 v[194:197], v161 offset:49152
	ds_read_b128 v[198:201], v161 offset:50176
	ds_read_b128 v[202:205], v161 offset:51200
	ds_read_b128 v[206:209], v161 offset:52224
	ds_read_b128 v[210:213], v161 offset:53248
	ds_read_b128 v[214:217], v161 offset:54272
	ds_read_b128 v[218:221], v161 offset:55296
	ds_read_b128 v[222:225], v161 offset:56320
	s_setprio 0
	global_load_lds_dwordx4 v[226:227], off
	s_add_i32 m0, s46, 0x2000
	s_add_u32 s44, s44, 0x80080
	v_lshl_add_u64 v[226:227], v[228:229], 0, s[18:19]
	s_addc_u32 s45, s45, 0
	s_add_i32 s46, s64, s26
	global_load_lds_dwordx4 v[226:227], off
	v_lshl_add_u64 v[226:227], s[44:45], 0, v[130:131]
	s_mov_b32 m0, s46
	s_nop 0
	global_load_lds_dwordx4 v[226:227], off
	v_lshl_add_u64 v[226:227], s[44:45], 0, v[134:135]
	s_add_i32 m0, s46, 0x2000
	s_nop 0
	global_load_lds_dwordx4 v[226:227], off
	v_lshl_add_u64 v[226:227], v[230:231], 0, s[18:19]
	s_mov_b32 m0, s50
	s_nop 0
	global_load_lds_dwordx4 v[226:227], off
	v_lshl_add_u64 v[226:227], v[232:233], 0, s[18:19]
	s_mov_b32 m0, s51
	s_nop 0
	global_load_lds_dwordx4 v[226:227], off
	s_waitcnt vmcnt(8)
	s_waitcnt lgkmcnt(0)
	s_barrier
	v_mfma_f32_16x16x32_bf16 v[60:63], v[154:157], v[194:197], v[60:63]
	v_mfma_f32_16x16x32_bf16 v[56:59], v[168:171], v[194:197], v[56:59]
	v_mfma_f32_16x16x32_bf16 v[44:47], v[154:157], v[202:205], v[44:47]
	v_mfma_f32_16x16x32_bf16 v[40:43], v[168:171], v[202:205], v[40:43]
	v_mfma_f32_16x16x32_bf16 v[28:31], v[154:157], v[210:213], v[28:31]
	v_mfma_f32_16x16x32_bf16 v[24:27], v[168:171], v[210:213], v[24:27]
	v_mfma_f32_16x16x32_bf16 v[12:15], v[154:157], v[218:221], v[12:15]
	v_mfma_f32_16x16x32_bf16 v[8:11], v[168:171], v[218:221], v[8:11]
	v_mfma_f32_16x16x32_bf16 v[60:63], v[164:167], v[198:201], v[60:63]
	v_mfma_f32_16x16x32_bf16 v[56:59], v[172:175], v[198:201], v[56:59]
	v_mfma_f32_16x16x32_bf16 v[44:47], v[164:167], v[206:209], v[44:47]
	v_mfma_f32_16x16x32_bf16 v[40:43], v[172:175], v[206:209], v[40:43]
	v_mfma_f32_16x16x32_bf16 v[28:31], v[164:167], v[214:217], v[28:31]
	v_mfma_f32_16x16x32_bf16 v[24:27], v[172:175], v[214:217], v[24:27]
	v_mfma_f32_16x16x32_bf16 v[12:15], v[164:167], v[222:225], v[12:15]
	v_mfma_f32_16x16x32_bf16 v[8:11], v[172:175], v[222:225], v[8:11]
	v_mfma_f32_16x16x32_bf16 v[52:55], v[176:179], v[194:197], v[52:55]
	v_mfma_f32_16x16x32_bf16 v[48:51], v[184:187], v[194:197], v[48:51]
	v_mfma_f32_16x16x32_bf16 v[36:39], v[176:179], v[202:205], v[36:39]
	v_mfma_f32_16x16x32_bf16 v[32:35], v[184:187], v[202:205], v[32:35]
	v_mfma_f32_16x16x32_bf16 v[20:23], v[176:179], v[210:213], v[20:23]
	v_mfma_f32_16x16x32_bf16 v[16:19], v[184:187], v[210:213], v[16:19]
	v_mfma_f32_16x16x32_bf16 v[4:7], v[176:179], v[218:221], v[4:7]
	v_mfma_f32_16x16x32_bf16 v[0:3], v[184:187], v[218:221], v[0:3]
	v_mfma_f32_16x16x32_bf16 v[52:55], v[180:183], v[198:201], v[52:55]
	v_mfma_f32_16x16x32_bf16 v[48:51], v[190:193], v[198:201], v[48:51]
	v_mfma_f32_16x16x32_bf16 v[36:39], v[180:183], v[206:209], v[36:39]
	v_mfma_f32_16x16x32_bf16 v[32:35], v[190:193], v[206:209], v[32:35]
	v_mfma_f32_16x16x32_bf16 v[20:23], v[180:183], v[214:217], v[20:23]
	v_mfma_f32_16x16x32_bf16 v[16:19], v[190:193], v[214:217], v[16:19]
	v_mfma_f32_16x16x32_bf16 v[4:7], v[180:183], v[222:225], v[4:7]
	v_mfma_f32_16x16x32_bf16 v[0:3], v[190:193], v[222:225], v[0:3]
	s_barrier
	s_add_i32 s62, s62, 2
	s_add_u32 s10, s10, 0x100
	s_addc_u32 s11, s11, 0
	s_add_u32 s60, s60, 0x100
	s_addc_u32 s61, s61, 0
	s_cmp_gt_u32 s62, 29
	s_cbranch_scc0 .LBB0_838
	s_and_b64 vcc, exec, s[20:21]
	s_cbranch_vccnz .LBB0_843
	v_lshl_add_u32 v154, s6, 8, v158
	s_cmp_gt_i32 s42, 3
	s_mov_b64 s[6:7], -1
	s_cbranch_scc1 .LBB0_844

.LBB0_947:
	s_setprio 2
	ds_read_b128 v[154:157], v137
	ds_read_b128 v[158:161], v137 offset:1024
	ds_read_b128 v[174:177], v137 offset:2048
	ds_read_b128 v[178:181], v137 offset:3072
	ds_read_b128 v[182:185], v170
	ds_read_b128 v[190:193], v170 offset:1024
	ds_read_b128 v[194:197], v170 offset:2048
	ds_read_b128 v[198:201], v170 offset:3072
	s_add_u32 s34, s10, 0xfffe0080
	s_addc_u32 s35, s11, -1
	s_cmp_eq_u32 s53, 4
	s_cselect_b32 s37, s5, s35
	s_cselect_b32 s36, s9, s34
	s_cselect_b32 s35, s13, s52
	s_cselect_b32 s34, s16, s51
	v_lshl_add_u64 v[186:187], s[10:11], 0, v[146:147]
	s_add_i32 m0, s15, 0xc000
	ds_read_b128 v[202:205], v171
	ds_read_b128 v[206:209], v171 offset:1024
	ds_read_b128 v[210:213], v171 offset:2048
	ds_read_b128 v[214:217], v171 offset:3072
	ds_read_b128 v[218:221], v171 offset:4096
	ds_read_b128 v[222:225], v171 offset:5120
	ds_read_b128 v[226:229], v171 offset:6144
	ds_read_b128 v[230:233], v171 offset:7168
	s_setprio 0
	global_load_lds_dwordx4 v[186:187], off
	v_lshl_add_u64 v[186:187], s[10:11], 0, v[148:149]
	s_add_i32 m0, s15, 0xe000
	s_nop 0
	global_load_lds_dwordx4 v[186:187], off
	s_waitcnt vmcnt(8)
	s_waitcnt lgkmcnt(0)
	s_barrier
	v_mfma_f32_16x16x32_bf16 v[124:127], v[154:157], v[202:205], v[124:127]
	v_mfma_f32_16x16x32_bf16 v[120:123], v[174:177], v[202:205], v[120:123]
	v_mfma_f32_16x16x32_bf16 v[108:111], v[154:157], v[210:213], v[108:111]
	v_mfma_f32_16x16x32_bf16 v[104:107], v[174:177], v[210:213], v[104:107]
	v_mfma_f32_16x16x32_bf16 v[92:95], v[154:157], v[218:221], v[92:95]
	v_mfma_f32_16x16x32_bf16 v[88:91], v[174:177], v[218:221], v[88:91]
	v_mfma_f32_16x16x32_bf16 v[76:79], v[154:157], v[226:229], v[76:79]
	v_mfma_f32_16x16x32_bf16 v[72:75], v[174:177], v[226:229], v[72:75]
	v_mfma_f32_16x16x32_bf16 v[124:127], v[158:161], v[206:209], v[124:127]
	v_mfma_f32_16x16x32_bf16 v[120:123], v[178:181], v[206:209], v[120:123]
	v_mfma_f32_16x16x32_bf16 v[108:111], v[158:161], v[214:217], v[108:111]
	v_mfma_f32_16x16x32_bf16 v[104:107], v[178:181], v[214:217], v[104:107]
	v_mfma_f32_16x16x32_bf16 v[92:95], v[158:161], v[222:225], v[92:95]
	v_mfma_f32_16x16x32_bf16 v[88:91], v[178:181], v[222:225], v[88:91]
	v_mfma_f32_16x16x32_bf16 v[76:79], v[158:161], v[230:233], v[76:79]
	v_mfma_f32_16x16x32_bf16 v[72:75], v[178:181], v[230:233], v[72:75]
	v_mfma_f32_16x16x32_bf16 v[116:119], v[182:185], v[202:205], v[116:119]
	v_mfma_f32_16x16x32_bf16 v[112:115], v[194:197], v[202:205], v[112:115]
	v_mfma_f32_16x16x32_bf16 v[100:103], v[182:185], v[210:213], v[100:103]
	v_mfma_f32_16x16x32_bf16 v[96:99], v[194:197], v[210:213], v[96:99]
	v_mfma_f32_16x16x32_bf16 v[84:87], v[182:185], v[218:221], v[84:87]
	v_mfma_f32_16x16x32_bf16 v[80:83], v[194:197], v[218:221], v[80:83]
	v_mfma_f32_16x16x32_bf16 v[68:71], v[182:185], v[226:229], v[68:71]
	v_mfma_f32_16x16x32_bf16 v[64:67], v[194:197], v[226:229], v[64:67]
	v_mfma_f32_16x16x32_bf16 v[116:119], v[190:193], v[206:209], v[116:119]
	v_mfma_f32_16x16x32_bf16 v[112:115], v[198:201], v[206:209], v[112:115]
	v_mfma_f32_16x16x32_bf16 v[100:103], v[190:193], v[214:217], v[100:103]
	v_mfma_f32_16x16x32_bf16 v[96:99], v[198:201], v[214:217], v[96:99]
	v_mfma_f32_16x16x32_bf16 v[84:87], v[190:193], v[222:225], v[84:87]
	v_mfma_f32_16x16x32_bf16 v[80:83], v[198:201], v[222:225], v[80:83]
	v_mfma_f32_16x16x32_bf16 v[68:71], v[190:193], v[230:233], v[68:71]
	v_mfma_f32_16x16x32_bf16 v[64:67], v[198:201], v[230:233], v[64:67]
	s_barrier
	s_add_i32 s54, s47, s26
	v_lshl_add_u64 v[186:187], s[34:35], 0, v[130:131]
	s_mov_b32 m0, s54
	s_setprio 2
	ds_read_b128 v[202:205], v171 offset:16384
	ds_read_b128 v[206:209], v171 offset:17408
	ds_read_b128 v[210:213], v171 offset:18432
	ds_read_b128 v[214:217], v171 offset:19456
	ds_read_b128 v[218:221], v171 offset:20480
	ds_read_b128 v[222:225], v171 offset:21504
	ds_read_b128 v[226:229], v171 offset:22528
	ds_read_b128 v[230:233], v171 offset:23552
	s_setprio 0
	global_load_lds_dwordx4 v[186:187], off
	s_add_i32 m0, s54, 0x2000
	s_add_u32 s54, s34, 0x20000
	v_lshl_add_u64 v[234:235], s[34:35], 0, v[134:135]
	s_addc_u32 s55, s35, 0
	s_add_i32 s58, s48, s26
	global_load_lds_dwordx4 v[234:235], off
	v_lshl_add_u64 v[236:237], s[54:55], 0, v[130:131]
	s_mov_b32 m0, s58
	v_lshl_add_u64 v[238:239], s[36:37], 0, v[132:133]
	global_load_lds_dwordx4 v[236:237], off
	v_lshl_add_u64 v[236:237], s[54:55], 0, v[134:135]
	s_add_i32 m0, s58, 0x2000
	s_nop 0
	global_load_lds_dwordx4 v[236:237], off
	v_lshl_add_u64 v[236:237], s[36:37], 0, v[128:129]
	s_mov_b32 m0, s15
	s_nop 0
	global_load_lds_dwordx4 v[236:237], off
	s_mov_b32 m0, s27
	s_nop 0
	global_load_lds_dwordx4 v[238:239], off
	s_waitcnt vmcnt(8)
	s_waitcnt lgkmcnt(0)
	s_barrier
	v_mfma_f32_16x16x32_bf16 v[60:63], v[154:157], v[202:205], v[60:63]
	v_mfma_f32_16x16x32_bf16 v[56:59], v[174:177], v[202:205], v[56:59]
	v_mfma_f32_16x16x32_bf16 v[44:47], v[154:157], v[210:213], v[44:47]
	v_mfma_f32_16x16x32_bf16 v[40:43], v[174:177], v[210:213], v[40:43]
	v_mfma_f32_16x16x32_bf16 v[28:31], v[154:157], v[218:221], v[28:31]
	v_mfma_f32_16x16x32_bf16 v[24:27], v[174:177], v[218:221], v[24:27]
	v_mfma_f32_16x16x32_bf16 v[12:15], v[154:157], v[226:229], v[12:15]
	v_mfma_f32_16x16x32_bf16 v[8:11], v[174:177], v[226:229], v[8:11]
	v_mfma_f32_16x16x32_bf16 v[60:63], v[158:161], v[206:209], v[60:63]
	v_mfma_f32_16x16x32_bf16 v[56:59], v[178:181], v[206:209], v[56:59]
	v_mfma_f32_16x16x32_bf16 v[44:47], v[158:161], v[214:217], v[44:47]
	v_mfma_f32_16x16x32_bf16 v[40:43], v[178:181], v[214:217], v[40:43]
	v_mfma_f32_16x16x32_bf16 v[28:31], v[158:161], v[222:225], v[28:31]
	v_mfma_f32_16x16x32_bf16 v[24:27], v[178:181], v[222:225], v[24:27]
	v_mfma_f32_16x16x32_bf16 v[12:15], v[158:161], v[230:233], v[12:15]
	v_mfma_f32_16x16x32_bf16 v[8:11], v[178:181], v[230:233], v[8:11]
	v_mfma_f32_16x16x32_bf16 v[52:55], v[182:185], v[202:205], v[52:55]
	v_mfma_f32_16x16x32_bf16 v[48:51], v[194:197], v[202:205], v[48:51]
	v_mfma_f32_16x16x32_bf16 v[36:39], v[182:185], v[210:213], v[36:39]
	v_mfma_f32_16x16x32_bf16 v[32:35], v[194:197], v[210:213], v[32:35]
	v_mfma_f32_16x16x32_bf16 v[20:23], v[182:185], v[218:221], v[20:23]
	v_mfma_f32_16x16x32_bf16 v[16:19], v[194:197], v[218:221], v[16:19]
	v_mfma_f32_16x16x32_bf16 v[4:7], v[182:185], v[226:229], v[4:7]
	v_mfma_f32_16x16x32_bf16 v[0:3], v[194:197], v[226:229], v[0:3]
	v_mfma_f32_16x16x32_bf16 v[52:55], v[190:193], v[206:209], v[52:55]
	v_mfma_f32_16x16x32_bf16 v[48:51], v[198:201], v[206:209], v[48:51]
	v_mfma_f32_16x16x32_bf16 v[36:39], v[190:193], v[214:217], v[36:39]
	v_mfma_f32_16x16x32_bf16 v[32:35], v[198:201], v[214:217], v[32:35]
	v_mfma_f32_16x16x32_bf16 v[20:23], v[190:193], v[222:225], v[20:23]
	v_mfma_f32_16x16x32_bf16 v[16:19], v[198:201], v[222:225], v[16:19]
	v_mfma_f32_16x16x32_bf16 v[4:7], v[190:193], v[230:233], v[4:7]
	v_mfma_f32_16x16x32_bf16 v[0:3], v[198:201], v[230:233], v[0:3]
	s_barrier
	s_add_i32 s54, 0, 0x18000
	v_add_u32_e32 v138, s54, v169
	s_add_i32 s55, 0, 0x1c000
	s_setprio 2
	ds_read_b128 v[154:157], v138
	ds_read_b128 v[158:161], v138 offset:1024
	ds_read_b128 v[174:177], v138 offset:2048
	ds_read_b128 v[178:181], v138 offset:3072
	v_add_u32_e32 v138, s55, v169
	ds_read_b128 v[182:185], v138
	ds_read_b128 v[190:193], v138 offset:1024
	ds_read_b128 v[194:197], v138 offset:2048
	ds_read_b128 v[198:201], v138 offset:3072
	s_add_u32 s36, s36, 0x20000
	s_addc_u32 s37, s37, 0
	s_mov_b32 m0, s38
	v_lshl_add_u64 v[240:241], s[36:37], 0, v[128:129]
	ds_read_b128 v[202:205], v171 offset:32768
	ds_read_b128 v[206:209], v171 offset:33792
	ds_read_b128 v[210:213], v171 offset:34816
	ds_read_b128 v[214:217], v171 offset:35840
	ds_read_b128 v[218:221], v171 offset:36864
	ds_read_b128 v[222:225], v171 offset:37888
	ds_read_b128 v[226:229], v171 offset:38912
	ds_read_b128 v[230:233], v171 offset:39936
	s_setprio 0
	global_load_lds_dwordx4 v[240:241], off
	v_lshl_add_u64 v[240:241], s[36:37], 0, v[132:133]
	s_mov_b32 m0, s39
	s_nop 0
	global_load_lds_dwordx4 v[240:241], off
	s_waitcnt vmcnt(8)
	s_waitcnt lgkmcnt(0)
	s_barrier
	v_mfma_f32_16x16x32_bf16 v[124:127], v[154:157], v[202:205], v[124:127]
	v_mfma_f32_16x16x32_bf16 v[120:123], v[174:177], v[202:205], v[120:123]
	v_mfma_f32_16x16x32_bf16 v[108:111], v[154:157], v[210:213], v[108:111]
	v_mfma_f32_16x16x32_bf16 v[104:107], v[174:177], v[210:213], v[104:107]
	v_mfma_f32_16x16x32_bf16 v[92:95], v[154:157], v[218:221], v[92:95]
	v_mfma_f32_16x16x32_bf16 v[88:91], v[174:177], v[218:221], v[88:91]
	v_mfma_f32_16x16x32_bf16 v[76:79], v[154:157], v[226:229], v[76:79]
	v_mfma_f32_16x16x32_bf16 v[72:75], v[174:177], v[226:229], v[72:75]
	v_mfma_f32_16x16x32_bf16 v[124:127], v[158:161], v[206:209], v[124:127]
	v_mfma_f32_16x16x32_bf16 v[120:123], v[178:181], v[206:209], v[120:123]
	v_mfma_f32_16x16x32_bf16 v[108:111], v[158:161], v[214:217], v[108:111]
	v_mfma_f32_16x16x32_bf16 v[104:107], v[178:181], v[214:217], v[104:107]
	v_mfma_f32_16x16x32_bf16 v[92:95], v[158:161], v[222:225], v[92:95]
	v_mfma_f32_16x16x32_bf16 v[88:91], v[178:181], v[222:225], v[88:91]
	v_mfma_f32_16x16x32_bf16 v[76:79], v[158:161], v[230:233], v[76:79]
	v_mfma_f32_16x16x32_bf16 v[72:75], v[178:181], v[230:233], v[72:75]
	v_mfma_f32_16x16x32_bf16 v[116:119], v[182:185], v[202:205], v[116:119]
	v_mfma_f32_16x16x32_bf16 v[112:115], v[194:197], v[202:205], v[112:115]
	v_mfma_f32_16x16x32_bf16 v[100:103], v[182:185], v[210:213], v[100:103]
	v_mfma_f32_16x16x32_bf16 v[96:99], v[194:197], v[210:213], v[96:99]
	v_mfma_f32_16x16x32_bf16 v[84:87], v[182:185], v[218:221], v[84:87]
	v_mfma_f32_16x16x32_bf16 v[80:83], v[194:197], v[218:221], v[80:83]
	v_mfma_f32_16x16x32_bf16 v[68:71], v[182:185], v[226:229], v[68:71]
	v_mfma_f32_16x16x32_bf16 v[64:67], v[194:197], v[226:229], v[64:67]
	v_mfma_f32_16x16x32_bf16 v[116:119], v[190:193], v[206:209], v[116:119]
	v_mfma_f32_16x16x32_bf16 v[112:115], v[198:201], v[206:209], v[112:115]
	v_mfma_f32_16x16x32_bf16 v[100:103], v[190:193], v[214:217], v[100:103]
	v_mfma_f32_16x16x32_bf16 v[96:99], v[198:201], v[214:217], v[96:99]
	v_mfma_f32_16x16x32_bf16 v[84:87], v[190:193], v[222:225], v[84:87]
	v_mfma_f32_16x16x32_bf16 v[80:83], v[198:201], v[222:225], v[80:83]
	v_mfma_f32_16x16x32_bf16 v[68:71], v[190:193], v[230:233], v[68:71]
	v_mfma_f32_16x16x32_bf16 v[64:67], v[198:201], v[230:233], v[64:67]
	s_barrier
	s_add_i32 s36, s54, s26
	v_lshl_add_u64 v[186:187], v[186:187], 0, s[20:21]
	s_mov_b32 m0, s36
	s_setprio 2
	ds_read_b128 v[202:205], v171 offset:49152
	ds_read_b128 v[206:209], v171 offset:50176
	ds_read_b128 v[210:213], v171 offset:51200
	ds_read_b128 v[214:217], v171 offset:52224
	ds_read_b128 v[218:221], v171 offset:53248
	ds_read_b128 v[222:225], v171 offset:54272
	ds_read_b128 v[226:229], v171 offset:55296
	ds_read_b128 v[230:233], v171 offset:56320
	s_setprio 0
	global_load_lds_dwordx4 v[186:187], off
	s_add_i32 m0, s36, 0x2000
	s_add_u32 s34, s34, 0x20080
	v_lshl_add_u64 v[186:187], v[234:235], 0, s[20:21]
	s_addc_u32 s35, s35, 0
	s_add_i32 s36, s55, s26
	global_load_lds_dwordx4 v[186:187], off
	v_lshl_add_u64 v[186:187], s[34:35], 0, v[130:131]
	s_mov_b32 m0, s36
	s_nop 0
	global_load_lds_dwordx4 v[186:187], off
	v_lshl_add_u64 v[186:187], s[34:35], 0, v[134:135]
	s_add_i32 m0, s36, 0x2000
	s_nop 0
	global_load_lds_dwordx4 v[186:187], off
	v_lshl_add_u64 v[186:187], v[236:237], 0, s[20:21]
	s_mov_b32 m0, s41
	s_nop 0
	global_load_lds_dwordx4 v[186:187], off
	v_lshl_add_u64 v[186:187], v[238:239], 0, s[20:21]
	s_mov_b32 m0, s42
	s_nop 0
	global_load_lds_dwordx4 v[186:187], off
	s_waitcnt vmcnt(8)
	s_waitcnt lgkmcnt(0)
	s_barrier
	v_mfma_f32_16x16x32_bf16 v[60:63], v[154:157], v[202:205], v[60:63]
	v_mfma_f32_16x16x32_bf16 v[56:59], v[174:177], v[202:205], v[56:59]
	v_mfma_f32_16x16x32_bf16 v[44:47], v[154:157], v[210:213], v[44:47]
	v_mfma_f32_16x16x32_bf16 v[40:43], v[174:177], v[210:213], v[40:43]
	v_mfma_f32_16x16x32_bf16 v[28:31], v[154:157], v[218:221], v[28:31]
	v_mfma_f32_16x16x32_bf16 v[24:27], v[174:177], v[218:221], v[24:27]
	v_mfma_f32_16x16x32_bf16 v[12:15], v[154:157], v[226:229], v[12:15]
	v_mfma_f32_16x16x32_bf16 v[8:11], v[174:177], v[226:229], v[8:11]
	v_mfma_f32_16x16x32_bf16 v[60:63], v[158:161], v[206:209], v[60:63]
	v_mfma_f32_16x16x32_bf16 v[56:59], v[178:181], v[206:209], v[56:59]
	v_mfma_f32_16x16x32_bf16 v[44:47], v[158:161], v[214:217], v[44:47]
	v_mfma_f32_16x16x32_bf16 v[40:43], v[178:181], v[214:217], v[40:43]
	v_mfma_f32_16x16x32_bf16 v[28:31], v[158:161], v[222:225], v[28:31]
	v_mfma_f32_16x16x32_bf16 v[24:27], v[178:181], v[222:225], v[24:27]
	v_mfma_f32_16x16x32_bf16 v[12:15], v[158:161], v[230:233], v[12:15]
	v_mfma_f32_16x16x32_bf16 v[8:11], v[178:181], v[230:233], v[8:11]
	v_mfma_f32_16x16x32_bf16 v[52:55], v[182:185], v[202:205], v[52:55]
	v_mfma_f32_16x16x32_bf16 v[48:51], v[194:197], v[202:205], v[48:51]
	v_mfma_f32_16x16x32_bf16 v[36:39], v[182:185], v[210:213], v[36:39]
	v_mfma_f32_16x16x32_bf16 v[32:35], v[194:197], v[210:213], v[32:35]
	v_mfma_f32_16x16x32_bf16 v[20:23], v[182:185], v[218:221], v[20:23]
	v_mfma_f32_16x16x32_bf16 v[16:19], v[194:197], v[218:221], v[16:19]
	v_mfma_f32_16x16x32_bf16 v[4:7], v[182:185], v[226:229], v[4:7]
	v_mfma_f32_16x16x32_bf16 v[0:3], v[194:197], v[226:229], v[0:3]
	v_mfma_f32_16x16x32_bf16 v[52:55], v[190:193], v[206:209], v[52:55]
	v_mfma_f32_16x16x32_bf16 v[48:51], v[198:201], v[206:209], v[48:51]
	v_mfma_f32_16x16x32_bf16 v[36:39], v[190:193], v[214:217], v[36:39]
	v_mfma_f32_16x16x32_bf16 v[32:35], v[198:201], v[214:217], v[32:35]
	v_mfma_f32_16x16x32_bf16 v[20:23], v[190:193], v[222:225], v[20:23]
	v_mfma_f32_16x16x32_bf16 v[16:19], v[198:201], v[222:225], v[16:19]
	v_mfma_f32_16x16x32_bf16 v[4:7], v[190:193], v[230:233], v[4:7]
	v_mfma_f32_16x16x32_bf16 v[0:3], v[198:201], v[230:233], v[0:3]
	s_barrier
	s_add_i32 s53, s53, 2
	s_add_u32 s10, s10, 0x100
	s_addc_u32 s11, s11, 0
	s_add_u32 s51, s51, 0x100
	s_addc_u32 s52, s52, 0
	s_cmp_gt_u32 s53, 5
	s_cbranch_scc0 .LBB0_947
	s_and_b64 vcc, exec, s[22:23]
	s_cbranch_vccz .LBB0_950
	s_barrier

.LBB0_1037:
	s_setprio 2
	ds_read_b128 v[148:151], v160
	ds_read_b128 v[152:155], v160 offset:1024
	ds_read_b128 v[166:169], v160 offset:2048
	ds_read_b128 v[170:173], v160 offset:3072
	ds_read_b128 v[174:177], v161
	ds_read_b128 v[178:181], v161 offset:1024
	ds_read_b128 v[182:185], v161 offset:2048
	ds_read_b128 v[190:193], v161 offset:3072
	s_add_u32 s34, s10, 0xfffe0080
	s_addc_u32 s35, s11, -1
	s_cmp_eq_u32 s51, 4
	s_cselect_b32 s37, s5, s35
	s_cselect_b32 s36, s12, s34
	s_cselect_b32 s35, s23, s50
	s_cselect_b32 s34, s27, s49
	v_lshl_add_u64 v[156:157], s[10:11], 0, v[140:141]
	s_add_i32 m0, s9, 0xc000
	ds_read_b128 v[194:197], v162
	ds_read_b128 v[198:201], v162 offset:1024
	ds_read_b128 v[202:205], v162 offset:2048
	ds_read_b128 v[206:209], v162 offset:3072
	ds_read_b128 v[210:213], v162 offset:4096
	ds_read_b128 v[214:217], v162 offset:5120
	ds_read_b128 v[218:221], v162 offset:6144
	ds_read_b128 v[222:225], v162 offset:7168
	s_setprio 0
	global_load_lds_dwordx4 v[156:157], off
	v_lshl_add_u64 v[156:157], s[10:11], 0, v[142:143]
	s_add_i32 m0, s9, 0xe000
	s_nop 0
	global_load_lds_dwordx4 v[156:157], off
	s_waitcnt vmcnt(8)
	s_waitcnt lgkmcnt(0)
	s_barrier
	v_mfma_f32_16x16x32_bf16 v[124:127], v[148:151], v[194:197], v[124:127]
	v_mfma_f32_16x16x32_bf16 v[120:123], v[166:169], v[194:197], v[120:123]
	v_mfma_f32_16x16x32_bf16 v[108:111], v[148:151], v[202:205], v[108:111]
	v_mfma_f32_16x16x32_bf16 v[104:107], v[166:169], v[202:205], v[104:107]
	v_mfma_f32_16x16x32_bf16 v[92:95], v[148:151], v[210:213], v[92:95]
	v_mfma_f32_16x16x32_bf16 v[88:91], v[166:169], v[210:213], v[88:91]
	v_mfma_f32_16x16x32_bf16 v[76:79], v[148:151], v[218:221], v[76:79]
	v_mfma_f32_16x16x32_bf16 v[72:75], v[166:169], v[218:221], v[72:75]
	v_mfma_f32_16x16x32_bf16 v[124:127], v[152:155], v[198:201], v[124:127]
	v_mfma_f32_16x16x32_bf16 v[120:123], v[170:173], v[198:201], v[120:123]
	v_mfma_f32_16x16x32_bf16 v[108:111], v[152:155], v[206:209], v[108:111]
	v_mfma_f32_16x16x32_bf16 v[104:107], v[170:173], v[206:209], v[104:107]
	v_mfma_f32_16x16x32_bf16 v[92:95], v[152:155], v[214:217], v[92:95]
	v_mfma_f32_16x16x32_bf16 v[88:91], v[170:173], v[214:217], v[88:91]
	v_mfma_f32_16x16x32_bf16 v[76:79], v[152:155], v[222:225], v[76:79]
	v_mfma_f32_16x16x32_bf16 v[72:75], v[170:173], v[222:225], v[72:75]
	v_mfma_f32_16x16x32_bf16 v[116:119], v[174:177], v[194:197], v[116:119]
	v_mfma_f32_16x16x32_bf16 v[112:115], v[182:185], v[194:197], v[112:115]
	v_mfma_f32_16x16x32_bf16 v[100:103], v[174:177], v[202:205], v[100:103]
	v_mfma_f32_16x16x32_bf16 v[96:99], v[182:185], v[202:205], v[96:99]
	v_mfma_f32_16x16x32_bf16 v[84:87], v[174:177], v[210:213], v[84:87]
	v_mfma_f32_16x16x32_bf16 v[80:83], v[182:185], v[210:213], v[80:83]
	v_mfma_f32_16x16x32_bf16 v[68:71], v[174:177], v[218:221], v[68:71]
	v_mfma_f32_16x16x32_bf16 v[64:67], v[182:185], v[218:221], v[64:67]
	v_mfma_f32_16x16x32_bf16 v[116:119], v[178:181], v[198:201], v[116:119]
	v_mfma_f32_16x16x32_bf16 v[112:115], v[190:193], v[198:201], v[112:115]
	v_mfma_f32_16x16x32_bf16 v[100:103], v[178:181], v[206:209], v[100:103]
	v_mfma_f32_16x16x32_bf16 v[96:99], v[190:193], v[206:209], v[96:99]
	v_mfma_f32_16x16x32_bf16 v[84:87], v[178:181], v[214:217], v[84:87]
	v_mfma_f32_16x16x32_bf16 v[80:83], v[190:193], v[214:217], v[80:83]
	v_mfma_f32_16x16x32_bf16 v[68:71], v[178:181], v[222:225], v[68:71]
	v_mfma_f32_16x16x32_bf16 v[64:67], v[190:193], v[222:225], v[64:67]
	s_barrier
	s_add_i32 s52, s45, s24
	v_lshl_add_u64 v[156:157], s[34:35], 0, v[130:131]
	s_mov_b32 m0, s52
	s_setprio 2
	ds_read_b128 v[194:197], v162 offset:16384
	ds_read_b128 v[198:201], v162 offset:17408
	ds_read_b128 v[202:205], v162 offset:18432
	ds_read_b128 v[206:209], v162 offset:19456
	ds_read_b128 v[210:213], v162 offset:20480
	ds_read_b128 v[214:217], v162 offset:21504
	ds_read_b128 v[218:221], v162 offset:22528
	ds_read_b128 v[222:225], v162 offset:23552
	s_setprio 0
	global_load_lds_dwordx4 v[156:157], off
	s_add_i32 m0, s52, 0x2000
	s_add_u32 s52, s34, 0x20000
	v_lshl_add_u64 v[186:187], s[34:35], 0, v[134:135]
	s_addc_u32 s53, s35, 0
	s_add_i32 s54, s46, s24
	global_load_lds_dwordx4 v[186:187], off
	v_lshl_add_u64 v[226:227], s[52:53], 0, v[130:131]
	s_mov_b32 m0, s54
	v_lshl_add_u64 v[228:229], s[36:37], 0, v[132:133]
	global_load_lds_dwordx4 v[226:227], off
	v_lshl_add_u64 v[226:227], s[52:53], 0, v[134:135]
	s_add_i32 m0, s54, 0x2000
	s_nop 0
	global_load_lds_dwordx4 v[226:227], off
	v_lshl_add_u64 v[226:227], s[36:37], 0, v[128:129]
	s_mov_b32 m0, s9
	s_nop 0
	global_load_lds_dwordx4 v[226:227], off
	s_mov_b32 m0, s25
	s_nop 0
	global_load_lds_dwordx4 v[228:229], off
	s_waitcnt vmcnt(8)
	s_waitcnt lgkmcnt(0)
	s_barrier
	v_mfma_f32_16x16x32_bf16 v[60:63], v[148:151], v[194:197], v[60:63]
	v_mfma_f32_16x16x32_bf16 v[56:59], v[166:169], v[194:197], v[56:59]
	v_mfma_f32_16x16x32_bf16 v[44:47], v[148:151], v[202:205], v[44:47]
	v_mfma_f32_16x16x32_bf16 v[40:43], v[166:169], v[202:205], v[40:43]
	v_mfma_f32_16x16x32_bf16 v[28:31], v[148:151], v[210:213], v[28:31]
	v_mfma_f32_16x16x32_bf16 v[24:27], v[166:169], v[210:213], v[24:27]
	v_mfma_f32_16x16x32_bf16 v[12:15], v[148:151], v[218:221], v[12:15]
	v_mfma_f32_16x16x32_bf16 v[8:11], v[166:169], v[218:221], v[8:11]
	v_mfma_f32_16x16x32_bf16 v[60:63], v[152:155], v[198:201], v[60:63]
	v_mfma_f32_16x16x32_bf16 v[56:59], v[170:173], v[198:201], v[56:59]
	v_mfma_f32_16x16x32_bf16 v[44:47], v[152:155], v[206:209], v[44:47]
	v_mfma_f32_16x16x32_bf16 v[40:43], v[170:173], v[206:209], v[40:43]
	v_mfma_f32_16x16x32_bf16 v[28:31], v[152:155], v[214:217], v[28:31]
	v_mfma_f32_16x16x32_bf16 v[24:27], v[170:173], v[214:217], v[24:27]
	v_mfma_f32_16x16x32_bf16 v[12:15], v[152:155], v[222:225], v[12:15]
	v_mfma_f32_16x16x32_bf16 v[8:11], v[170:173], v[222:225], v[8:11]
	v_mfma_f32_16x16x32_bf16 v[52:55], v[174:177], v[194:197], v[52:55]
	v_mfma_f32_16x16x32_bf16 v[48:51], v[182:185], v[194:197], v[48:51]
	v_mfma_f32_16x16x32_bf16 v[36:39], v[174:177], v[202:205], v[36:39]
	v_mfma_f32_16x16x32_bf16 v[32:35], v[182:185], v[202:205], v[32:35]
	v_mfma_f32_16x16x32_bf16 v[20:23], v[174:177], v[210:213], v[20:23]
	v_mfma_f32_16x16x32_bf16 v[16:19], v[182:185], v[210:213], v[16:19]
	v_mfma_f32_16x16x32_bf16 v[4:7], v[174:177], v[218:221], v[4:7]
	v_mfma_f32_16x16x32_bf16 v[0:3], v[182:185], v[218:221], v[0:3]
	v_mfma_f32_16x16x32_bf16 v[52:55], v[178:181], v[198:201], v[52:55]
	v_mfma_f32_16x16x32_bf16 v[48:51], v[190:193], v[198:201], v[48:51]
	v_mfma_f32_16x16x32_bf16 v[36:39], v[178:181], v[206:209], v[36:39]
	v_mfma_f32_16x16x32_bf16 v[32:35], v[190:193], v[206:209], v[32:35]
	v_mfma_f32_16x16x32_bf16 v[20:23], v[178:181], v[214:217], v[20:23]
	v_mfma_f32_16x16x32_bf16 v[16:19], v[190:193], v[214:217], v[16:19]
	v_mfma_f32_16x16x32_bf16 v[4:7], v[178:181], v[222:225], v[4:7]
	v_mfma_f32_16x16x32_bf16 v[0:3], v[190:193], v[222:225], v[0:3]
	s_barrier
	s_add_i32 s52, 0, 0x18000
	v_add_u32_e32 v165, s52, v159
	s_add_i32 s53, 0, 0x1c000
	s_setprio 2
	ds_read_b128 v[148:151], v165
	ds_read_b128 v[152:155], v165 offset:1024
	ds_read_b128 v[166:169], v165 offset:2048
	ds_read_b128 v[170:173], v165 offset:3072
	v_add_u32_e32 v165, s53, v159
	ds_read_b128 v[174:177], v165
	ds_read_b128 v[178:181], v165 offset:1024
	ds_read_b128 v[182:185], v165 offset:2048
	ds_read_b128 v[190:193], v165 offset:3072
	s_add_u32 s36, s36, 0x20000
	s_addc_u32 s37, s37, 0
	s_mov_b32 m0, s38
	v_lshl_add_u64 v[230:231], s[36:37], 0, v[128:129]
	ds_read_b128 v[194:197], v162 offset:32768
	ds_read_b128 v[198:201], v162 offset:33792
	ds_read_b128 v[202:205], v162 offset:34816
	ds_read_b128 v[206:209], v162 offset:35840
	ds_read_b128 v[210:213], v162 offset:36864
	ds_read_b128 v[214:217], v162 offset:37888
	ds_read_b128 v[218:221], v162 offset:38912
	ds_read_b128 v[222:225], v162 offset:39936
	s_setprio 0
	global_load_lds_dwordx4 v[230:231], off
	v_lshl_add_u64 v[230:231], s[36:37], 0, v[132:133]
	s_mov_b32 m0, s39
	s_nop 0
	global_load_lds_dwordx4 v[230:231], off
	s_waitcnt vmcnt(8)
	s_waitcnt lgkmcnt(0)
	s_barrier
	v_mfma_f32_16x16x32_bf16 v[124:127], v[148:151], v[194:197], v[124:127]
	v_mfma_f32_16x16x32_bf16 v[120:123], v[166:169], v[194:197], v[120:123]
	v_mfma_f32_16x16x32_bf16 v[108:111], v[148:151], v[202:205], v[108:111]
	v_mfma_f32_16x16x32_bf16 v[104:107], v[166:169], v[202:205], v[104:107]
	v_mfma_f32_16x16x32_bf16 v[92:95], v[148:151], v[210:213], v[92:95]
	v_mfma_f32_16x16x32_bf16 v[88:91], v[166:169], v[210:213], v[88:91]
	v_mfma_f32_16x16x32_bf16 v[76:79], v[148:151], v[218:221], v[76:79]
	v_mfma_f32_16x16x32_bf16 v[72:75], v[166:169], v[218:221], v[72:75]
	v_mfma_f32_16x16x32_bf16 v[124:127], v[152:155], v[198:201], v[124:127]
	v_mfma_f32_16x16x32_bf16 v[120:123], v[170:173], v[198:201], v[120:123]
	v_mfma_f32_16x16x32_bf16 v[108:111], v[152:155], v[206:209], v[108:111]
	v_mfma_f32_16x16x32_bf16 v[104:107], v[170:173], v[206:209], v[104:107]
	v_mfma_f32_16x16x32_bf16 v[92:95], v[152:155], v[214:217], v[92:95]
	v_mfma_f32_16x16x32_bf16 v[88:91], v[170:173], v[214:217], v[88:91]
	v_mfma_f32_16x16x32_bf16 v[76:79], v[152:155], v[222:225], v[76:79]
	v_mfma_f32_16x16x32_bf16 v[72:75], v[170:173], v[222:225], v[72:75]
	v_mfma_f32_16x16x32_bf16 v[116:119], v[174:177], v[194:197], v[116:119]
	v_mfma_f32_16x16x32_bf16 v[112:115], v[182:185], v[194:197], v[112:115]
	v_mfma_f32_16x16x32_bf16 v[100:103], v[174:177], v[202:205], v[100:103]
	v_mfma_f32_16x16x32_bf16 v[96:99], v[182:185], v[202:205], v[96:99]
	v_mfma_f32_16x16x32_bf16 v[84:87], v[174:177], v[210:213], v[84:87]
	v_mfma_f32_16x16x32_bf16 v[80:83], v[182:185], v[210:213], v[80:83]
	v_mfma_f32_16x16x32_bf16 v[68:71], v[174:177], v[218:221], v[68:71]
	v_mfma_f32_16x16x32_bf16 v[64:67], v[182:185], v[218:221], v[64:67]
	v_mfma_f32_16x16x32_bf16 v[116:119], v[178:181], v[198:201], v[116:119]
	v_mfma_f32_16x16x32_bf16 v[112:115], v[190:193], v[198:201], v[112:115]
	v_mfma_f32_16x16x32_bf16 v[100:103], v[178:181], v[206:209], v[100:103]
	v_mfma_f32_16x16x32_bf16 v[96:99], v[190:193], v[206:209], v[96:99]
	v_mfma_f32_16x16x32_bf16 v[84:87], v[178:181], v[214:217], v[84:87]
	v_mfma_f32_16x16x32_bf16 v[80:83], v[190:193], v[214:217], v[80:83]
	v_mfma_f32_16x16x32_bf16 v[68:71], v[178:181], v[222:225], v[68:71]
	v_mfma_f32_16x16x32_bf16 v[64:67], v[190:193], v[222:225], v[64:67]
	s_barrier
	s_add_i32 s36, s52, s24
	v_lshl_add_u64 v[156:157], v[156:157], 0, s[16:17]
	s_mov_b32 m0, s36
	s_setprio 2
	ds_read_b128 v[194:197], v162 offset:49152
	ds_read_b128 v[198:201], v162 offset:50176
	ds_read_b128 v[202:205], v162 offset:51200
	ds_read_b128 v[206:209], v162 offset:52224
	ds_read_b128 v[210:213], v162 offset:53248
	ds_read_b128 v[214:217], v162 offset:54272
	ds_read_b128 v[218:221], v162 offset:55296
	ds_read_b128 v[222:225], v162 offset:56320
	s_setprio 0
	global_load_lds_dwordx4 v[156:157], off
	s_add_i32 m0, s36, 0x2000
	s_add_u32 s34, s34, 0x20080
	v_lshl_add_u64 v[156:157], v[186:187], 0, s[16:17]
	s_addc_u32 s35, s35, 0
	s_add_i32 s36, s53, s24
	global_load_lds_dwordx4 v[156:157], off
	v_lshl_add_u64 v[156:157], s[34:35], 0, v[130:131]
	s_mov_b32 m0, s36
	s_nop 0
	global_load_lds_dwordx4 v[156:157], off
	v_lshl_add_u64 v[156:157], s[34:35], 0, v[134:135]
	s_add_i32 m0, s36, 0x2000
	s_nop 0
	global_load_lds_dwordx4 v[156:157], off
	v_lshl_add_u64 v[156:157], v[226:227], 0, s[16:17]
	s_mov_b32 m0, s41
	s_nop 0
	global_load_lds_dwordx4 v[156:157], off
	v_lshl_add_u64 v[156:157], v[228:229], 0, s[16:17]
	s_mov_b32 m0, s42
	s_nop 0
	global_load_lds_dwordx4 v[156:157], off
	s_waitcnt vmcnt(8)
	s_waitcnt lgkmcnt(0)
	s_barrier
	v_mfma_f32_16x16x32_bf16 v[60:63], v[148:151], v[194:197], v[60:63]
	v_mfma_f32_16x16x32_bf16 v[56:59], v[166:169], v[194:197], v[56:59]
	v_mfma_f32_16x16x32_bf16 v[44:47], v[148:151], v[202:205], v[44:47]
	v_mfma_f32_16x16x32_bf16 v[40:43], v[166:169], v[202:205], v[40:43]
	v_mfma_f32_16x16x32_bf16 v[28:31], v[148:151], v[210:213], v[28:31]
	v_mfma_f32_16x16x32_bf16 v[24:27], v[166:169], v[210:213], v[24:27]
	v_mfma_f32_16x16x32_bf16 v[12:15], v[148:151], v[218:221], v[12:15]
	v_mfma_f32_16x16x32_bf16 v[8:11], v[166:169], v[218:221], v[8:11]
	v_mfma_f32_16x16x32_bf16 v[60:63], v[152:155], v[198:201], v[60:63]
	v_mfma_f32_16x16x32_bf16 v[56:59], v[170:173], v[198:201], v[56:59]
	v_mfma_f32_16x16x32_bf16 v[44:47], v[152:155], v[206:209], v[44:47]
	v_mfma_f32_16x16x32_bf16 v[40:43], v[170:173], v[206:209], v[40:43]
	v_mfma_f32_16x16x32_bf16 v[28:31], v[152:155], v[214:217], v[28:31]
	v_mfma_f32_16x16x32_bf16 v[24:27], v[170:173], v[214:217], v[24:27]
	v_mfma_f32_16x16x32_bf16 v[12:15], v[152:155], v[222:225], v[12:15]
	v_mfma_f32_16x16x32_bf16 v[8:11], v[170:173], v[222:225], v[8:11]
	v_mfma_f32_16x16x32_bf16 v[52:55], v[174:177], v[194:197], v[52:55]
	v_mfma_f32_16x16x32_bf16 v[48:51], v[182:185], v[194:197], v[48:51]
	v_mfma_f32_16x16x32_bf16 v[36:39], v[174:177], v[202:205], v[36:39]
	v_mfma_f32_16x16x32_bf16 v[32:35], v[182:185], v[202:205], v[32:35]
	v_mfma_f32_16x16x32_bf16 v[20:23], v[174:177], v[210:213], v[20:23]
	v_mfma_f32_16x16x32_bf16 v[16:19], v[182:185], v[210:213], v[16:19]
	v_mfma_f32_16x16x32_bf16 v[4:7], v[174:177], v[218:221], v[4:7]
	v_mfma_f32_16x16x32_bf16 v[0:3], v[182:185], v[218:221], v[0:3]
	v_mfma_f32_16x16x32_bf16 v[52:55], v[178:181], v[198:201], v[52:55]
	v_mfma_f32_16x16x32_bf16 v[48:51], v[190:193], v[198:201], v[48:51]
	v_mfma_f32_16x16x32_bf16 v[36:39], v[178:181], v[206:209], v[36:39]
	v_mfma_f32_16x16x32_bf16 v[32:35], v[190:193], v[206:209], v[32:35]
	v_mfma_f32_16x16x32_bf16 v[20:23], v[178:181], v[214:217], v[20:23]
	v_mfma_f32_16x16x32_bf16 v[16:19], v[190:193], v[214:217], v[16:19]
	v_mfma_f32_16x16x32_bf16 v[4:7], v[178:181], v[222:225], v[4:7]
	v_mfma_f32_16x16x32_bf16 v[0:3], v[190:193], v[222:225], v[0:3]
	s_barrier
	s_add_i32 s51, s51, 2
	s_add_u32 s10, s10, 0x100
	s_addc_u32 s11, s11, 0
	s_add_u32 s49, s49, 0x100
	s_addc_u32 s50, s50, 0
	s_cmp_gt_u32 s51, 5
	s_cbranch_scc0 .LBB0_1037
	s_and_b64 vcc, exec, s[18:19]
	s_cbranch_vccz .LBB0_1040
	s_barrier

.LBB0_1452:
	s_setprio 2
	ds_read_b128 v[128:131], v177
	ds_read_b128 v[132:135], v177 offset:1024
	ds_read_b128 v[136:139], v177 offset:2048
	ds_read_b128 v[140:143], v177 offset:3072
	ds_read_b128 v[160:163], v178
	ds_read_b128 v[164:167], v178 offset:1024
	ds_read_b128 v[168:171], v178 offset:2048
	ds_read_b128 v[182:185], v178 offset:3072
	s_add_u32 s28, s26, 0xfff80080
	s_addc_u32 s29, s27, -1
	s_cmp_eq_u32 s50, 28
	s_cselect_b32 s31, s15, s29
	s_cselect_b32 s30, s23, s28
	s_cselect_b32 s29, s17, s49
	s_cselect_b32 s28, s25, s48
	v_lshl_add_u64 v[172:173], s[26:27], 0, v[152:153]
	s_add_i32 m0, s34, 0xc000
	ds_read_b128 v[190:193], v179
	ds_read_b128 v[194:197], v179 offset:1024
	ds_read_b128 v[198:201], v179 offset:2048
	ds_read_b128 v[202:205], v179 offset:3072
	ds_read_b128 v[206:209], v179 offset:4096
	ds_read_b128 v[210:213], v179 offset:5120
	ds_read_b128 v[214:217], v179 offset:6144
	ds_read_b128 v[218:221], v179 offset:7168
	s_setprio 0
	global_load_lds_dwordx4 v[172:173], off
	v_lshl_add_u64 v[172:173], s[26:27], 0, v[154:155]
	s_add_i32 m0, s34, 0xe000
	s_nop 0
	global_load_lds_dwordx4 v[172:173], off
	s_waitcnt vmcnt(8)
	s_waitcnt lgkmcnt(0)
	s_barrier
	v_mfma_f32_16x16x32_bf16 v[124:127], v[128:131], v[190:193], v[124:127]
	v_mfma_f32_16x16x32_bf16 v[120:123], v[136:139], v[190:193], v[120:123]
	v_mfma_f32_16x16x32_bf16 v[108:111], v[128:131], v[198:201], v[108:111]
	v_mfma_f32_16x16x32_bf16 v[104:107], v[136:139], v[198:201], v[104:107]
	v_mfma_f32_16x16x32_bf16 v[92:95], v[128:131], v[206:209], v[92:95]
	v_mfma_f32_16x16x32_bf16 v[88:91], v[136:139], v[206:209], v[88:91]
	v_mfma_f32_16x16x32_bf16 v[76:79], v[128:131], v[214:217], v[76:79]
	v_mfma_f32_16x16x32_bf16 v[72:75], v[136:139], v[214:217], v[72:75]
	v_mfma_f32_16x16x32_bf16 v[124:127], v[132:135], v[194:197], v[124:127]
	v_mfma_f32_16x16x32_bf16 v[120:123], v[140:143], v[194:197], v[120:123]
	v_mfma_f32_16x16x32_bf16 v[108:111], v[132:135], v[202:205], v[108:111]
	v_mfma_f32_16x16x32_bf16 v[104:107], v[140:143], v[202:205], v[104:107]
	v_mfma_f32_16x16x32_bf16 v[92:95], v[132:135], v[210:213], v[92:95]
	v_mfma_f32_16x16x32_bf16 v[88:91], v[140:143], v[210:213], v[88:91]
	v_mfma_f32_16x16x32_bf16 v[76:79], v[132:135], v[218:221], v[76:79]
	v_mfma_f32_16x16x32_bf16 v[72:75], v[140:143], v[218:221], v[72:75]
	v_mfma_f32_16x16x32_bf16 v[116:119], v[160:163], v[190:193], v[116:119]
	v_mfma_f32_16x16x32_bf16 v[112:115], v[168:171], v[190:193], v[112:115]
	v_mfma_f32_16x16x32_bf16 v[100:103], v[160:163], v[198:201], v[100:103]
	v_mfma_f32_16x16x32_bf16 v[96:99], v[168:171], v[198:201], v[96:99]
	v_mfma_f32_16x16x32_bf16 v[84:87], v[160:163], v[206:209], v[84:87]
	v_mfma_f32_16x16x32_bf16 v[80:83], v[168:171], v[206:209], v[80:83]
	v_mfma_f32_16x16x32_bf16 v[68:71], v[160:163], v[214:217], v[68:71]
	v_mfma_f32_16x16x32_bf16 v[64:67], v[168:171], v[214:217], v[64:67]
	v_mfma_f32_16x16x32_bf16 v[116:119], v[164:167], v[194:197], v[116:119]
	v_mfma_f32_16x16x32_bf16 v[112:115], v[182:185], v[194:197], v[112:115]
	v_mfma_f32_16x16x32_bf16 v[100:103], v[164:167], v[202:205], v[100:103]
	v_mfma_f32_16x16x32_bf16 v[96:99], v[182:185], v[202:205], v[96:99]
	v_mfma_f32_16x16x32_bf16 v[84:87], v[164:167], v[210:213], v[84:87]
	v_mfma_f32_16x16x32_bf16 v[80:83], v[182:185], v[210:213], v[80:83]
	v_mfma_f32_16x16x32_bf16 v[68:71], v[164:167], v[218:221], v[68:71]
	v_mfma_f32_16x16x32_bf16 v[64:67], v[182:185], v[218:221], v[64:67]
	s_barrier
	s_add_i32 s51, s45, s33
	v_lshl_add_u64 v[172:173], s[28:29], 0, v[146:147]
	s_mov_b32 m0, s51
	s_setprio 2
	ds_read_b128 v[190:193], v179 offset:16384
	ds_read_b128 v[194:197], v179 offset:17408
	ds_read_b128 v[198:201], v179 offset:18432
	ds_read_b128 v[202:205], v179 offset:19456
	ds_read_b128 v[206:209], v179 offset:20480
	ds_read_b128 v[210:213], v179 offset:21504
	ds_read_b128 v[214:217], v179 offset:22528
	ds_read_b128 v[218:221], v179 offset:23552
	s_setprio 0
	global_load_lds_dwordx4 v[172:173], off
	s_add_i32 m0, s51, 0x2000
	s_add_u32 s52, s28, 0x80000
	v_lshl_add_u64 v[186:187], s[28:29], 0, v[150:151]
	s_addc_u32 s53, s29, 0
	s_add_i32 s51, s46, s33
	global_load_lds_dwordx4 v[186:187], off
	v_lshl_add_u64 v[222:223], s[52:53], 0, v[146:147]
	s_mov_b32 m0, s51
	v_lshl_add_u64 v[224:225], s[30:31], 0, v[148:149]
	global_load_lds_dwordx4 v[222:223], off
	v_lshl_add_u64 v[222:223], s[52:53], 0, v[150:151]
	s_add_i32 m0, s51, 0x2000
	s_nop 0
	global_load_lds_dwordx4 v[222:223], off
	v_lshl_add_u64 v[222:223], s[30:31], 0, v[144:145]
	s_mov_b32 m0, s34
	s_nop 0
	global_load_lds_dwordx4 v[222:223], off
	s_mov_b32 m0, s35
	s_nop 0
	global_load_lds_dwordx4 v[224:225], off
	s_waitcnt vmcnt(8)
	s_waitcnt lgkmcnt(0)
	s_barrier
	v_mfma_f32_16x16x32_bf16 v[60:63], v[128:131], v[190:193], v[60:63]
	v_mfma_f32_16x16x32_bf16 v[56:59], v[136:139], v[190:193], v[56:59]
	v_mfma_f32_16x16x32_bf16 v[44:47], v[128:131], v[198:201], v[44:47]
	v_mfma_f32_16x16x32_bf16 v[40:43], v[136:139], v[198:201], v[40:43]
	v_mfma_f32_16x16x32_bf16 v[28:31], v[128:131], v[206:209], v[28:31]
	v_mfma_f32_16x16x32_bf16 v[24:27], v[136:139], v[206:209], v[24:27]
	v_mfma_f32_16x16x32_bf16 v[12:15], v[128:131], v[214:217], v[12:15]
	v_mfma_f32_16x16x32_bf16 v[8:11], v[136:139], v[214:217], v[8:11]
	v_mfma_f32_16x16x32_bf16 v[60:63], v[132:135], v[194:197], v[60:63]
	v_mfma_f32_16x16x32_bf16 v[56:59], v[140:143], v[194:197], v[56:59]
	v_mfma_f32_16x16x32_bf16 v[44:47], v[132:135], v[202:205], v[44:47]
	v_mfma_f32_16x16x32_bf16 v[40:43], v[140:143], v[202:205], v[40:43]
	v_mfma_f32_16x16x32_bf16 v[28:31], v[132:135], v[210:213], v[28:31]
	v_mfma_f32_16x16x32_bf16 v[24:27], v[140:143], v[210:213], v[24:27]
	v_mfma_f32_16x16x32_bf16 v[12:15], v[132:135], v[218:221], v[12:15]
	v_mfma_f32_16x16x32_bf16 v[8:11], v[140:143], v[218:221], v[8:11]
	v_mfma_f32_16x16x32_bf16 v[52:55], v[160:163], v[190:193], v[52:55]
	v_mfma_f32_16x16x32_bf16 v[48:51], v[168:171], v[190:193], v[48:51]
	v_mfma_f32_16x16x32_bf16 v[36:39], v[160:163], v[198:201], v[36:39]
	v_mfma_f32_16x16x32_bf16 v[32:35], v[168:171], v[198:201], v[32:35]
	v_mfma_f32_16x16x32_bf16 v[20:23], v[160:163], v[206:209], v[20:23]
	v_mfma_f32_16x16x32_bf16 v[16:19], v[168:171], v[206:209], v[16:19]
	v_mfma_f32_16x16x32_bf16 v[4:7], v[160:163], v[214:217], v[4:7]
	v_mfma_f32_16x16x32_bf16 v[0:3], v[168:171], v[214:217], v[0:3]
	v_mfma_f32_16x16x32_bf16 v[52:55], v[164:167], v[194:197], v[52:55]
	v_mfma_f32_16x16x32_bf16 v[48:51], v[182:185], v[194:197], v[48:51]
	v_mfma_f32_16x16x32_bf16 v[36:39], v[164:167], v[202:205], v[36:39]
	v_mfma_f32_16x16x32_bf16 v[32:35], v[182:185], v[202:205], v[32:35]
	v_mfma_f32_16x16x32_bf16 v[20:23], v[164:167], v[210:213], v[20:23]
	v_mfma_f32_16x16x32_bf16 v[16:19], v[182:185], v[210:213], v[16:19]
	v_mfma_f32_16x16x32_bf16 v[4:7], v[164:167], v[218:221], v[4:7]
	v_mfma_f32_16x16x32_bf16 v[0:3], v[182:185], v[218:221], v[0:3]
	s_barrier
	s_add_i32 s51, 0, 0x18000
	s_add_i32 s52, 0, 0x1c000
	v_add_u32_e32 v140, s51, v175
	v_add_u32_e32 v181, s52, v175
	s_setprio 2
	ds_read_b128 v[128:131], v140
	ds_read_b128 v[132:135], v140 offset:1024
	ds_read_b128 v[136:139], v140 offset:2048
	ds_read_b128 v[140:143], v140 offset:3072
	ds_read_b128 v[160:163], v181
	ds_read_b128 v[164:167], v181 offset:1024
	ds_read_b128 v[168:171], v181 offset:2048
	ds_read_b128 v[182:185], v181 offset:3072
	s_add_u32 s30, s30, 0x80000
	s_addc_u32 s31, s31, 0
	s_mov_b32 m0, s36
	v_lshl_add_u64 v[226:227], s[30:31], 0, v[144:145]
	ds_read_b128 v[190:193], v179 offset:32768
	ds_read_b128 v[194:197], v179 offset:33792
	ds_read_b128 v[198:201], v179 offset:34816
	ds_read_b128 v[202:205], v179 offset:35840
	ds_read_b128 v[206:209], v179 offset:36864
	ds_read_b128 v[210:213], v179 offset:37888
	ds_read_b128 v[214:217], v179 offset:38912
	ds_read_b128 v[218:221], v179 offset:39936
	s_setprio 0
	global_load_lds_dwordx4 v[226:227], off
	v_lshl_add_u64 v[226:227], s[30:31], 0, v[148:149]
	s_mov_b32 m0, s37
	s_nop 0
	global_load_lds_dwordx4 v[226:227], off
	s_waitcnt vmcnt(8)
	s_waitcnt lgkmcnt(0)
	s_barrier
	v_mfma_f32_16x16x32_bf16 v[124:127], v[128:131], v[190:193], v[124:127]
	v_mfma_f32_16x16x32_bf16 v[120:123], v[136:139], v[190:193], v[120:123]
	v_mfma_f32_16x16x32_bf16 v[108:111], v[128:131], v[198:201], v[108:111]
	v_mfma_f32_16x16x32_bf16 v[104:107], v[136:139], v[198:201], v[104:107]
	v_mfma_f32_16x16x32_bf16 v[92:95], v[128:131], v[206:209], v[92:95]
	v_mfma_f32_16x16x32_bf16 v[88:91], v[136:139], v[206:209], v[88:91]
	v_mfma_f32_16x16x32_bf16 v[76:79], v[128:131], v[214:217], v[76:79]
	v_mfma_f32_16x16x32_bf16 v[72:75], v[136:139], v[214:217], v[72:75]
	v_mfma_f32_16x16x32_bf16 v[124:127], v[132:135], v[194:197], v[124:127]
	v_mfma_f32_16x16x32_bf16 v[120:123], v[140:143], v[194:197], v[120:123]
	v_mfma_f32_16x16x32_bf16 v[108:111], v[132:135], v[202:205], v[108:111]
	v_mfma_f32_16x16x32_bf16 v[104:107], v[140:143], v[202:205], v[104:107]
	v_mfma_f32_16x16x32_bf16 v[92:95], v[132:135], v[210:213], v[92:95]
	v_mfma_f32_16x16x32_bf16 v[88:91], v[140:143], v[210:213], v[88:91]
	v_mfma_f32_16x16x32_bf16 v[76:79], v[132:135], v[218:221], v[76:79]
	v_mfma_f32_16x16x32_bf16 v[72:75], v[140:143], v[218:221], v[72:75]
	v_mfma_f32_16x16x32_bf16 v[116:119], v[160:163], v[190:193], v[116:119]
	v_mfma_f32_16x16x32_bf16 v[112:115], v[168:171], v[190:193], v[112:115]
	v_mfma_f32_16x16x32_bf16 v[100:103], v[160:163], v[198:201], v[100:103]
	v_mfma_f32_16x16x32_bf16 v[96:99], v[168:171], v[198:201], v[96:99]
	v_mfma_f32_16x16x32_bf16 v[84:87], v[160:163], v[206:209], v[84:87]
	v_mfma_f32_16x16x32_bf16 v[80:83], v[168:171], v[206:209], v[80:83]
	v_mfma_f32_16x16x32_bf16 v[68:71], v[160:163], v[214:217], v[68:71]
	v_mfma_f32_16x16x32_bf16 v[64:67], v[168:171], v[214:217], v[64:67]
	v_mfma_f32_16x16x32_bf16 v[116:119], v[164:167], v[194:197], v[116:119]
	v_mfma_f32_16x16x32_bf16 v[112:115], v[182:185], v[194:197], v[112:115]
	v_mfma_f32_16x16x32_bf16 v[100:103], v[164:167], v[202:205], v[100:103]
	v_mfma_f32_16x16x32_bf16 v[96:99], v[182:185], v[202:205], v[96:99]
	v_mfma_f32_16x16x32_bf16 v[84:87], v[164:167], v[210:213], v[84:87]
	v_mfma_f32_16x16x32_bf16 v[80:83], v[182:185], v[210:213], v[80:83]
	v_mfma_f32_16x16x32_bf16 v[68:71], v[164:167], v[218:221], v[68:71]
	v_mfma_f32_16x16x32_bf16 v[64:67], v[182:185], v[218:221], v[64:67]
	s_barrier
	s_add_i32 s30, s51, s33
	v_lshl_add_u64 v[172:173], v[172:173], 0, s[8:9]
	s_mov_b32 m0, s30
	s_setprio 2
	ds_read_b128 v[190:193], v179 offset:49152
	ds_read_b128 v[194:197], v179 offset:50176
	ds_read_b128 v[198:201], v179 offset:51200
	ds_read_b128 v[202:205], v179 offset:52224
	ds_read_b128 v[206:209], v179 offset:53248
	ds_read_b128 v[210:213], v179 offset:54272
	ds_read_b128 v[214:217], v179 offset:55296
	ds_read_b128 v[218:221], v179 offset:56320
	s_setprio 0
	global_load_lds_dwordx4 v[172:173], off
	s_add_i32 m0, s30, 0x2000
	s_add_u32 s28, s28, 0x80080
	v_lshl_add_u64 v[172:173], v[186:187], 0, s[8:9]
	s_addc_u32 s29, s29, 0
	s_add_i32 s30, s52, s33
	global_load_lds_dwordx4 v[172:173], off
	v_lshl_add_u64 v[172:173], s[28:29], 0, v[146:147]
	s_mov_b32 m0, s30
	s_nop 0
	global_load_lds_dwordx4 v[172:173], off
	v_lshl_add_u64 v[172:173], s[28:29], 0, v[150:151]
	s_add_i32 m0, s30, 0x2000
	s_nop 0
	global_load_lds_dwordx4 v[172:173], off
	v_lshl_add_u64 v[172:173], v[222:223], 0, s[8:9]
	s_mov_b32 m0, s41
	s_nop 0
	global_load_lds_dwordx4 v[172:173], off
	v_lshl_add_u64 v[172:173], v[224:225], 0, s[8:9]
	s_mov_b32 m0, s42
	s_nop 0
	global_load_lds_dwordx4 v[172:173], off
	s_waitcnt vmcnt(8)
	s_waitcnt lgkmcnt(0)
	s_barrier
	v_mfma_f32_16x16x32_bf16 v[60:63], v[128:131], v[190:193], v[60:63]
	v_mfma_f32_16x16x32_bf16 v[56:59], v[136:139], v[190:193], v[56:59]
	v_mfma_f32_16x16x32_bf16 v[44:47], v[128:131], v[198:201], v[44:47]
	v_mfma_f32_16x16x32_bf16 v[40:43], v[136:139], v[198:201], v[40:43]
	v_mfma_f32_16x16x32_bf16 v[28:31], v[128:131], v[206:209], v[28:31]
	v_mfma_f32_16x16x32_bf16 v[24:27], v[136:139], v[206:209], v[24:27]
	v_mfma_f32_16x16x32_bf16 v[12:15], v[128:131], v[214:217], v[12:15]
	v_mfma_f32_16x16x32_bf16 v[8:11], v[136:139], v[214:217], v[8:11]
	v_mfma_f32_16x16x32_bf16 v[60:63], v[132:135], v[194:197], v[60:63]
	v_mfma_f32_16x16x32_bf16 v[56:59], v[140:143], v[194:197], v[56:59]
	v_mfma_f32_16x16x32_bf16 v[44:47], v[132:135], v[202:205], v[44:47]
	v_mfma_f32_16x16x32_bf16 v[40:43], v[140:143], v[202:205], v[40:43]
	v_mfma_f32_16x16x32_bf16 v[28:31], v[132:135], v[210:213], v[28:31]
	v_mfma_f32_16x16x32_bf16 v[24:27], v[140:143], v[210:213], v[24:27]
	v_mfma_f32_16x16x32_bf16 v[12:15], v[132:135], v[218:221], v[12:15]
	v_mfma_f32_16x16x32_bf16 v[8:11], v[140:143], v[218:221], v[8:11]
	v_mfma_f32_16x16x32_bf16 v[52:55], v[160:163], v[190:193], v[52:55]
	v_mfma_f32_16x16x32_bf16 v[48:51], v[168:171], v[190:193], v[48:51]
	v_mfma_f32_16x16x32_bf16 v[36:39], v[160:163], v[198:201], v[36:39]
	v_mfma_f32_16x16x32_bf16 v[32:35], v[168:171], v[198:201], v[32:35]
	v_mfma_f32_16x16x32_bf16 v[20:23], v[160:163], v[206:209], v[20:23]
	v_mfma_f32_16x16x32_bf16 v[16:19], v[168:171], v[206:209], v[16:19]
	v_mfma_f32_16x16x32_bf16 v[4:7], v[160:163], v[214:217], v[4:7]
	v_mfma_f32_16x16x32_bf16 v[0:3], v[168:171], v[214:217], v[0:3]
	v_mfma_f32_16x16x32_bf16 v[52:55], v[164:167], v[194:197], v[52:55]
	v_mfma_f32_16x16x32_bf16 v[48:51], v[182:185], v[194:197], v[48:51]
	v_mfma_f32_16x16x32_bf16 v[36:39], v[164:167], v[202:205], v[36:39]
	v_mfma_f32_16x16x32_bf16 v[32:35], v[182:185], v[202:205], v[32:35]
	v_mfma_f32_16x16x32_bf16 v[20:23], v[164:167], v[210:213], v[20:23]
	v_mfma_f32_16x16x32_bf16 v[16:19], v[182:185], v[210:213], v[16:19]
	v_mfma_f32_16x16x32_bf16 v[4:7], v[164:167], v[218:221], v[4:7]
	v_mfma_f32_16x16x32_bf16 v[0:3], v[182:185], v[218:221], v[0:3]
	s_barrier
	s_add_i32 s50, s50, 2
	s_add_u32 s26, s26, 0x100
	s_addc_u32 s27, s27, 0
	s_add_u32 s48, s48, 0x100
	s_addc_u32 s49, s49, 0
	s_cmp_gt_u32 s50, 29
	s_cbranch_scc0 .LBB0_1452
	s_and_b64 vcc, exec, s[10:11]
	s_cbranch_vccz .LBB0_1455
	s_barrier

.LBB0_1539:
	s_setprio 2
	ds_read_b128 v[156:159], v151
	ds_read_b128 v[160:163], v151 offset:1024
	ds_read_b128 v[164:167], v151 offset:2048
	ds_read_b128 v[168:171], v151 offset:3072
	ds_read_b128 v[172:175], v152
	ds_read_b128 v[176:179], v152 offset:1024
	ds_read_b128 v[180:183], v152 offset:2048
	ds_read_b128 v[184:187], v152 offset:3072
	s_add_u32 s22, s20, 0xfff80080
	s_addc_u32 s23, s21, -1
	s_cmp_eq_u32 s48, 28
	s_cselect_b32 s25, s11, s23
	s_cselect_b32 s24, s44, s22
	s_cselect_b32 s23, s13, s47
	s_cselect_b32 s22, s45, s46
	v_lshl_add_u64 v[146:147], s[20:21], 0, v[138:139]
	s_add_i32 m0, s19, 0xc000
	ds_read_b128 v[190:193], v153
	ds_read_b128 v[194:197], v153 offset:1024
	ds_read_b128 v[198:201], v153 offset:2048
	ds_read_b128 v[202:205], v153 offset:3072
	ds_read_b128 v[206:209], v153 offset:4096
	ds_read_b128 v[210:213], v153 offset:5120
	ds_read_b128 v[214:217], v153 offset:6144
	ds_read_b128 v[218:221], v153 offset:7168
	s_setprio 0
	global_load_lds_dwordx4 v[146:147], off
	v_lshl_add_u64 v[146:147], s[20:21], 0, v[140:141]
	s_add_i32 m0, s19, 0xe000
	s_nop 0
	global_load_lds_dwordx4 v[146:147], off
	s_waitcnt vmcnt(8)
	s_waitcnt lgkmcnt(0)
	s_barrier
	v_mfma_f32_16x16x32_bf16 v[116:119], v[156:159], v[190:193], v[116:119]
	v_mfma_f32_16x16x32_bf16 v[112:115], v[164:167], v[190:193], v[112:115]
	v_mfma_f32_16x16x32_bf16 v[100:103], v[156:159], v[198:201], v[100:103]
	v_mfma_f32_16x16x32_bf16 v[96:99], v[164:167], v[198:201], v[96:99]
	v_mfma_f32_16x16x32_bf16 v[84:87], v[156:159], v[206:209], v[84:87]
	v_mfma_f32_16x16x32_bf16 v[80:83], v[164:167], v[206:209], v[80:83]
	v_mfma_f32_16x16x32_bf16 v[68:71], v[156:159], v[214:217], v[68:71]
	v_mfma_f32_16x16x32_bf16 v[64:67], v[164:167], v[214:217], v[64:67]
	v_mfma_f32_16x16x32_bf16 v[116:119], v[160:163], v[194:197], v[116:119]
	v_mfma_f32_16x16x32_bf16 v[112:115], v[168:171], v[194:197], v[112:115]
	v_mfma_f32_16x16x32_bf16 v[100:103], v[160:163], v[202:205], v[100:103]
	v_mfma_f32_16x16x32_bf16 v[96:99], v[168:171], v[202:205], v[96:99]
	v_mfma_f32_16x16x32_bf16 v[84:87], v[160:163], v[210:213], v[84:87]
	v_mfma_f32_16x16x32_bf16 v[80:83], v[168:171], v[210:213], v[80:83]
	v_mfma_f32_16x16x32_bf16 v[68:71], v[160:163], v[218:221], v[68:71]
	v_mfma_f32_16x16x32_bf16 v[64:67], v[168:171], v[218:221], v[64:67]
	v_mfma_f32_16x16x32_bf16 v[124:127], v[172:175], v[190:193], v[124:127]
	v_mfma_f32_16x16x32_bf16 v[120:123], v[180:183], v[190:193], v[120:123]
	v_mfma_f32_16x16x32_bf16 v[108:111], v[172:175], v[198:201], v[108:111]
	v_mfma_f32_16x16x32_bf16 v[104:107], v[180:183], v[198:201], v[104:107]
	v_mfma_f32_16x16x32_bf16 v[92:95], v[172:175], v[206:209], v[92:95]
	v_mfma_f32_16x16x32_bf16 v[88:91], v[180:183], v[206:209], v[88:91]
	v_mfma_f32_16x16x32_bf16 v[76:79], v[172:175], v[214:217], v[76:79]
	v_mfma_f32_16x16x32_bf16 v[72:75], v[180:183], v[214:217], v[72:75]
	v_mfma_f32_16x16x32_bf16 v[124:127], v[176:179], v[194:197], v[124:127]
	v_mfma_f32_16x16x32_bf16 v[120:123], v[184:187], v[194:197], v[120:123]
	v_mfma_f32_16x16x32_bf16 v[108:111], v[176:179], v[202:205], v[108:111]
	v_mfma_f32_16x16x32_bf16 v[104:107], v[184:187], v[202:205], v[104:107]
	v_mfma_f32_16x16x32_bf16 v[92:95], v[176:179], v[210:213], v[92:95]
	v_mfma_f32_16x16x32_bf16 v[88:91], v[184:187], v[210:213], v[88:91]
	v_mfma_f32_16x16x32_bf16 v[76:79], v[176:179], v[218:221], v[76:79]
	v_mfma_f32_16x16x32_bf16 v[72:75], v[184:187], v[218:221], v[72:75]
	s_barrier
	s_add_i32 s49, s40, s28
	v_lshl_add_u64 v[146:147], s[22:23], 0, v[132:133]
	s_mov_b32 m0, s49
	s_setprio 2
	ds_read_b128 v[190:193], v153 offset:16384
	ds_read_b128 v[194:197], v153 offset:17408
	ds_read_b128 v[198:201], v153 offset:18432
	ds_read_b128 v[202:205], v153 offset:19456
	ds_read_b128 v[206:209], v153 offset:20480
	ds_read_b128 v[210:213], v153 offset:21504
	ds_read_b128 v[214:217], v153 offset:22528
	ds_read_b128 v[218:221], v153 offset:23552
	s_setprio 0
	global_load_lds_dwordx4 v[146:147], off
	s_add_i32 m0, s49, 0x2000
	s_add_u32 s50, s22, 0x80000
	v_lshl_add_u64 v[222:223], s[22:23], 0, v[128:129]
	s_addc_u32 s51, s23, 0
	s_add_i32 s49, s41, s28
	global_load_lds_dwordx4 v[222:223], off
	v_lshl_add_u64 v[224:225], s[50:51], 0, v[132:133]
	s_mov_b32 m0, s49
	v_lshl_add_u64 v[226:227], s[24:25], 0, v[130:131]
	global_load_lds_dwordx4 v[224:225], off
	v_lshl_add_u64 v[224:225], s[50:51], 0, v[128:129]
	s_add_i32 m0, s49, 0x2000
	s_nop 0
	global_load_lds_dwordx4 v[224:225], off
	v_lshl_add_u64 v[224:225], s[24:25], 0, v[134:135]
	s_mov_b32 m0, s19
	s_nop 0
	global_load_lds_dwordx4 v[224:225], off
	s_mov_b32 m0, s30
	s_nop 0
	global_load_lds_dwordx4 v[226:227], off
	s_waitcnt vmcnt(8)
	s_waitcnt lgkmcnt(0)
	s_barrier
	v_mfma_f32_16x16x32_bf16 v[52:55], v[156:159], v[190:193], v[52:55]
	v_mfma_f32_16x16x32_bf16 v[48:51], v[164:167], v[190:193], v[48:51]
	v_mfma_f32_16x16x32_bf16 v[36:39], v[156:159], v[198:201], v[36:39]
	v_mfma_f32_16x16x32_bf16 v[32:35], v[164:167], v[198:201], v[32:35]
	v_mfma_f32_16x16x32_bf16 v[20:23], v[156:159], v[206:209], v[20:23]
	v_mfma_f32_16x16x32_bf16 v[16:19], v[164:167], v[206:209], v[16:19]
	v_mfma_f32_16x16x32_bf16 v[8:11], v[156:159], v[214:217], v[8:11]
	v_mfma_f32_16x16x32_bf16 v[0:3], v[164:167], v[214:217], v[0:3]
	v_mfma_f32_16x16x32_bf16 v[52:55], v[160:163], v[194:197], v[52:55]
	v_mfma_f32_16x16x32_bf16 v[48:51], v[168:171], v[194:197], v[48:51]
	v_mfma_f32_16x16x32_bf16 v[36:39], v[160:163], v[202:205], v[36:39]
	v_mfma_f32_16x16x32_bf16 v[32:35], v[168:171], v[202:205], v[32:35]
	v_mfma_f32_16x16x32_bf16 v[20:23], v[160:163], v[210:213], v[20:23]
	v_mfma_f32_16x16x32_bf16 v[16:19], v[168:171], v[210:213], v[16:19]
	v_mfma_f32_16x16x32_bf16 v[8:11], v[160:163], v[218:221], v[8:11]
	v_mfma_f32_16x16x32_bf16 v[0:3], v[168:171], v[218:221], v[0:3]
	v_mfma_f32_16x16x32_bf16 v[60:63], v[172:175], v[190:193], v[60:63]
	v_mfma_f32_16x16x32_bf16 v[56:59], v[180:183], v[190:193], v[56:59]
	v_mfma_f32_16x16x32_bf16 v[44:47], v[172:175], v[198:201], v[44:47]
	v_mfma_f32_16x16x32_bf16 v[40:43], v[180:183], v[198:201], v[40:43]
	v_mfma_f32_16x16x32_bf16 v[28:31], v[172:175], v[206:209], v[28:31]
	v_mfma_f32_16x16x32_bf16 v[24:27], v[180:183], v[206:209], v[24:27]
	v_mfma_f32_16x16x32_bf16 v[12:15], v[172:175], v[214:217], v[12:15]
	v_mfma_f32_16x16x32_bf16 v[4:7], v[180:183], v[214:217], v[4:7]
	v_mfma_f32_16x16x32_bf16 v[60:63], v[176:179], v[194:197], v[60:63]
	v_mfma_f32_16x16x32_bf16 v[56:59], v[184:187], v[194:197], v[56:59]
	v_mfma_f32_16x16x32_bf16 v[44:47], v[176:179], v[202:205], v[44:47]
	v_mfma_f32_16x16x32_bf16 v[40:43], v[184:187], v[202:205], v[40:43]
	v_mfma_f32_16x16x32_bf16 v[28:31], v[176:179], v[210:213], v[28:31]
	v_mfma_f32_16x16x32_bf16 v[24:27], v[184:187], v[210:213], v[24:27]
	v_mfma_f32_16x16x32_bf16 v[12:15], v[176:179], v[218:221], v[12:15]
	v_mfma_f32_16x16x32_bf16 v[4:7], v[184:187], v[218:221], v[4:7]
	s_barrier
	s_add_i32 s49, 0, 0x18000
	s_add_i32 s50, 0, 0x1c000
	v_add_u32_e32 v168, s49, v149
	v_add_u32_e32 v184, s50, v149
	s_setprio 2
	ds_read_b128 v[156:159], v168
	ds_read_b128 v[160:163], v168 offset:1024
	ds_read_b128 v[164:167], v168 offset:2048
	ds_read_b128 v[168:171], v168 offset:3072
	ds_read_b128 v[172:175], v184
	ds_read_b128 v[176:179], v184 offset:1024
	ds_read_b128 v[180:183], v184 offset:2048
	ds_read_b128 v[184:187], v184 offset:3072
	s_add_u32 s24, s24, 0x80000
	s_addc_u32 s25, s25, 0
	s_mov_b32 m0, s31
	v_lshl_add_u64 v[228:229], s[24:25], 0, v[134:135]
	ds_read_b128 v[190:193], v153 offset:32768
	ds_read_b128 v[194:197], v153 offset:33792
	ds_read_b128 v[198:201], v153 offset:34816
	ds_read_b128 v[202:205], v153 offset:35840
	ds_read_b128 v[206:209], v153 offset:36864
	ds_read_b128 v[210:213], v153 offset:37888
	ds_read_b128 v[214:217], v153 offset:38912
	ds_read_b128 v[218:221], v153 offset:39936
	s_setprio 0
	global_load_lds_dwordx4 v[228:229], off
	v_lshl_add_u64 v[228:229], s[24:25], 0, v[130:131]
	s_mov_b32 m0, s33
	s_nop 0
	global_load_lds_dwordx4 v[228:229], off
	s_waitcnt vmcnt(8)
	s_waitcnt lgkmcnt(0)
	s_barrier
	v_mfma_f32_16x16x32_bf16 v[116:119], v[156:159], v[190:193], v[116:119]
	v_mfma_f32_16x16x32_bf16 v[112:115], v[164:167], v[190:193], v[112:115]
	v_mfma_f32_16x16x32_bf16 v[100:103], v[156:159], v[198:201], v[100:103]
	v_mfma_f32_16x16x32_bf16 v[96:99], v[164:167], v[198:201], v[96:99]
	v_mfma_f32_16x16x32_bf16 v[84:87], v[156:159], v[206:209], v[84:87]
	v_mfma_f32_16x16x32_bf16 v[80:83], v[164:167], v[206:209], v[80:83]
	v_mfma_f32_16x16x32_bf16 v[68:71], v[156:159], v[214:217], v[68:71]
	v_mfma_f32_16x16x32_bf16 v[64:67], v[164:167], v[214:217], v[64:67]
	v_mfma_f32_16x16x32_bf16 v[116:119], v[160:163], v[194:197], v[116:119]
	v_mfma_f32_16x16x32_bf16 v[112:115], v[168:171], v[194:197], v[112:115]
	v_mfma_f32_16x16x32_bf16 v[100:103], v[160:163], v[202:205], v[100:103]
	v_mfma_f32_16x16x32_bf16 v[96:99], v[168:171], v[202:205], v[96:99]
	v_mfma_f32_16x16x32_bf16 v[84:87], v[160:163], v[210:213], v[84:87]
	v_mfma_f32_16x16x32_bf16 v[80:83], v[168:171], v[210:213], v[80:83]
	v_mfma_f32_16x16x32_bf16 v[68:71], v[160:163], v[218:221], v[68:71]
	v_mfma_f32_16x16x32_bf16 v[64:67], v[168:171], v[218:221], v[64:67]
	v_mfma_f32_16x16x32_bf16 v[124:127], v[172:175], v[190:193], v[124:127]
	v_mfma_f32_16x16x32_bf16 v[120:123], v[180:183], v[190:193], v[120:123]
	v_mfma_f32_16x16x32_bf16 v[108:111], v[172:175], v[198:201], v[108:111]
	v_mfma_f32_16x16x32_bf16 v[104:107], v[180:183], v[198:201], v[104:107]
	v_mfma_f32_16x16x32_bf16 v[92:95], v[172:175], v[206:209], v[92:95]
	v_mfma_f32_16x16x32_bf16 v[88:91], v[180:183], v[206:209], v[88:91]
	v_mfma_f32_16x16x32_bf16 v[76:79], v[172:175], v[214:217], v[76:79]
	v_mfma_f32_16x16x32_bf16 v[72:75], v[180:183], v[214:217], v[72:75]
	v_mfma_f32_16x16x32_bf16 v[124:127], v[176:179], v[194:197], v[124:127]
	v_mfma_f32_16x16x32_bf16 v[120:123], v[184:187], v[194:197], v[120:123]
	v_mfma_f32_16x16x32_bf16 v[108:111], v[176:179], v[202:205], v[108:111]
	v_mfma_f32_16x16x32_bf16 v[104:107], v[184:187], v[202:205], v[104:107]
	v_mfma_f32_16x16x32_bf16 v[92:95], v[176:179], v[210:213], v[92:95]
	v_mfma_f32_16x16x32_bf16 v[88:91], v[184:187], v[210:213], v[88:91]
	v_mfma_f32_16x16x32_bf16 v[76:79], v[176:179], v[218:221], v[76:79]
	v_mfma_f32_16x16x32_bf16 v[72:75], v[184:187], v[218:221], v[72:75]
	s_barrier
	s_add_i32 s24, s49, s28
	v_lshl_add_u64 v[146:147], v[146:147], 0, s[6:7]
	s_mov_b32 m0, s24
	s_setprio 2
	ds_read_b128 v[190:193], v153 offset:49152
	ds_read_b128 v[194:197], v153 offset:50176
	ds_read_b128 v[198:201], v153 offset:51200
	ds_read_b128 v[202:205], v153 offset:52224
	ds_read_b128 v[206:209], v153 offset:53248
	ds_read_b128 v[210:213], v153 offset:54272
	ds_read_b128 v[214:217], v153 offset:55296
	ds_read_b128 v[218:221], v153 offset:56320
	s_setprio 0
	global_load_lds_dwordx4 v[146:147], off
	s_add_i32 m0, s24, 0x2000
	s_add_u32 s22, s22, 0x80080
	v_lshl_add_u64 v[146:147], v[222:223], 0, s[6:7]
	s_addc_u32 s23, s23, 0
	s_add_i32 s24, s50, s28
	global_load_lds_dwordx4 v[146:147], off
	v_lshl_add_u64 v[146:147], s[22:23], 0, v[132:133]
	s_mov_b32 m0, s24
	s_nop 0
	global_load_lds_dwordx4 v[146:147], off
	v_lshl_add_u64 v[146:147], s[22:23], 0, v[128:129]
	s_add_i32 m0, s24, 0x2000
	s_nop 0
	global_load_lds_dwordx4 v[146:147], off
	v_lshl_add_u64 v[146:147], v[224:225], 0, s[6:7]
	s_mov_b32 m0, s36
	s_nop 0
	global_load_lds_dwordx4 v[146:147], off
	v_lshl_add_u64 v[146:147], v[226:227], 0, s[6:7]
	s_mov_b32 m0, s37
	s_nop 0
	global_load_lds_dwordx4 v[146:147], off
	s_waitcnt vmcnt(8)
	s_waitcnt lgkmcnt(0)
	s_barrier
	v_mfma_f32_16x16x32_bf16 v[52:55], v[156:159], v[190:193], v[52:55]
	v_mfma_f32_16x16x32_bf16 v[48:51], v[164:167], v[190:193], v[48:51]
	v_mfma_f32_16x16x32_bf16 v[36:39], v[156:159], v[198:201], v[36:39]
	v_mfma_f32_16x16x32_bf16 v[32:35], v[164:167], v[198:201], v[32:35]
	v_mfma_f32_16x16x32_bf16 v[20:23], v[156:159], v[206:209], v[20:23]
	v_mfma_f32_16x16x32_bf16 v[16:19], v[164:167], v[206:209], v[16:19]
	v_mfma_f32_16x16x32_bf16 v[8:11], v[156:159], v[214:217], v[8:11]
	v_mfma_f32_16x16x32_bf16 v[0:3], v[164:167], v[214:217], v[0:3]
	v_mfma_f32_16x16x32_bf16 v[52:55], v[160:163], v[194:197], v[52:55]
	v_mfma_f32_16x16x32_bf16 v[48:51], v[168:171], v[194:197], v[48:51]
	v_mfma_f32_16x16x32_bf16 v[36:39], v[160:163], v[202:205], v[36:39]
	v_mfma_f32_16x16x32_bf16 v[32:35], v[168:171], v[202:205], v[32:35]
	v_mfma_f32_16x16x32_bf16 v[20:23], v[160:163], v[210:213], v[20:23]
	v_mfma_f32_16x16x32_bf16 v[16:19], v[168:171], v[210:213], v[16:19]
	v_mfma_f32_16x16x32_bf16 v[8:11], v[160:163], v[218:221], v[8:11]
	v_mfma_f32_16x16x32_bf16 v[0:3], v[168:171], v[218:221], v[0:3]
	v_mfma_f32_16x16x32_bf16 v[60:63], v[172:175], v[190:193], v[60:63]
	v_mfma_f32_16x16x32_bf16 v[56:59], v[180:183], v[190:193], v[56:59]
	v_mfma_f32_16x16x32_bf16 v[44:47], v[172:175], v[198:201], v[44:47]
	v_mfma_f32_16x16x32_bf16 v[40:43], v[180:183], v[198:201], v[40:43]
	v_mfma_f32_16x16x32_bf16 v[28:31], v[172:175], v[206:209], v[28:31]
	v_mfma_f32_16x16x32_bf16 v[24:27], v[180:183], v[206:209], v[24:27]
	v_mfma_f32_16x16x32_bf16 v[12:15], v[172:175], v[214:217], v[12:15]
	v_mfma_f32_16x16x32_bf16 v[4:7], v[180:183], v[214:217], v[4:7]
	v_mfma_f32_16x16x32_bf16 v[60:63], v[176:179], v[194:197], v[60:63]
	v_mfma_f32_16x16x32_bf16 v[56:59], v[184:187], v[194:197], v[56:59]
	v_mfma_f32_16x16x32_bf16 v[44:47], v[176:179], v[202:205], v[44:47]
	v_mfma_f32_16x16x32_bf16 v[40:43], v[184:187], v[202:205], v[40:43]
	v_mfma_f32_16x16x32_bf16 v[28:31], v[176:179], v[210:213], v[28:31]
	v_mfma_f32_16x16x32_bf16 v[24:27], v[184:187], v[210:213], v[24:27]
	v_mfma_f32_16x16x32_bf16 v[12:15], v[176:179], v[218:221], v[12:15]
	v_mfma_f32_16x16x32_bf16 v[4:7], v[184:187], v[218:221], v[4:7]
	s_barrier
	s_add_i32 s48, s48, 2
	s_add_u32 s20, s20, 0x100
	s_addc_u32 s21, s21, 0
	s_add_u32 s46, s46, 0x100
	s_addc_u32 s47, s47, 0
	s_cmp_gt_u32 s48, 29
	s_cbranch_scc0 .LBB0_1539
	s_and_b64 vcc, exec, s[8:9]
	s_cbranch_vccz .LBB0_1542
	s_barrier

.LBB0_1624:
	s_setprio 2
	ds_read_b128 v[128:131], v177
	ds_read_b128 v[132:135], v177 offset:1024
	ds_read_b128 v[136:139], v177 offset:2048
	ds_read_b128 v[140:143], v177 offset:3072
	ds_read_b128 v[160:163], v178
	ds_read_b128 v[164:167], v178 offset:1024
	ds_read_b128 v[168:171], v178 offset:2048
	ds_read_b128 v[182:185], v178 offset:3072
	s_add_u32 s20, s18, 0xffea0080
	s_addc_u32 s21, s19, -1
	s_cmpk_eq_i32 s48, 0x54
	s_cselect_b32 s23, s1, s21
	s_cselect_b32 s22, s0, s20
	s_cselect_b32 s21, s17, s47
	s_cselect_b32 s20, s16, s46
	v_lshl_add_u64 v[172:173], s[18:19], 0, v[152:153]
	s_add_i32 m0, s27, 0xc000
	ds_read_b128 v[190:193], v179
	ds_read_b128 v[194:197], v179 offset:1024
	ds_read_b128 v[198:201], v179 offset:2048
	ds_read_b128 v[202:205], v179 offset:3072
	ds_read_b128 v[206:209], v179 offset:4096
	ds_read_b128 v[210:213], v179 offset:5120
	ds_read_b128 v[214:217], v179 offset:6144
	ds_read_b128 v[218:221], v179 offset:7168
	s_setprio 0
	global_load_lds_dwordx4 v[172:173], off
	v_lshl_add_u64 v[172:173], s[18:19], 0, v[154:155]
	s_add_i32 m0, s27, 0xe000
	s_nop 0
	global_load_lds_dwordx4 v[172:173], off
	s_waitcnt vmcnt(8)
	s_waitcnt lgkmcnt(0)
	s_barrier
	v_mfma_f32_16x16x32_bf16 v[124:127], v[128:131], v[190:193], v[124:127]
	v_mfma_f32_16x16x32_bf16 v[120:123], v[136:139], v[190:193], v[120:123]
	v_mfma_f32_16x16x32_bf16 v[108:111], v[128:131], v[198:201], v[108:111]
	v_mfma_f32_16x16x32_bf16 v[104:107], v[136:139], v[198:201], v[104:107]
	v_mfma_f32_16x16x32_bf16 v[92:95], v[128:131], v[206:209], v[92:95]
	v_mfma_f32_16x16x32_bf16 v[88:91], v[136:139], v[206:209], v[88:91]
	v_mfma_f32_16x16x32_bf16 v[76:79], v[128:131], v[214:217], v[76:79]
	v_mfma_f32_16x16x32_bf16 v[72:75], v[136:139], v[214:217], v[72:75]
	v_mfma_f32_16x16x32_bf16 v[124:127], v[132:135], v[194:197], v[124:127]
	v_mfma_f32_16x16x32_bf16 v[120:123], v[140:143], v[194:197], v[120:123]
	v_mfma_f32_16x16x32_bf16 v[108:111], v[132:135], v[202:205], v[108:111]
	v_mfma_f32_16x16x32_bf16 v[104:107], v[140:143], v[202:205], v[104:107]
	v_mfma_f32_16x16x32_bf16 v[92:95], v[132:135], v[210:213], v[92:95]
	v_mfma_f32_16x16x32_bf16 v[88:91], v[140:143], v[210:213], v[88:91]
	v_mfma_f32_16x16x32_bf16 v[76:79], v[132:135], v[218:221], v[76:79]
	v_mfma_f32_16x16x32_bf16 v[72:75], v[140:143], v[218:221], v[72:75]
	v_mfma_f32_16x16x32_bf16 v[116:119], v[160:163], v[190:193], v[116:119]
	v_mfma_f32_16x16x32_bf16 v[112:115], v[168:171], v[190:193], v[112:115]
	v_mfma_f32_16x16x32_bf16 v[100:103], v[160:163], v[198:201], v[100:103]
	v_mfma_f32_16x16x32_bf16 v[96:99], v[168:171], v[198:201], v[96:99]
	v_mfma_f32_16x16x32_bf16 v[84:87], v[160:163], v[206:209], v[84:87]
	v_mfma_f32_16x16x32_bf16 v[80:83], v[168:171], v[206:209], v[80:83]
	v_mfma_f32_16x16x32_bf16 v[68:71], v[160:163], v[214:217], v[68:71]
	v_mfma_f32_16x16x32_bf16 v[64:67], v[168:171], v[214:217], v[64:67]
	v_mfma_f32_16x16x32_bf16 v[116:119], v[164:167], v[194:197], v[116:119]
	v_mfma_f32_16x16x32_bf16 v[112:115], v[182:185], v[194:197], v[112:115]
	v_mfma_f32_16x16x32_bf16 v[100:103], v[164:167], v[202:205], v[100:103]
	v_mfma_f32_16x16x32_bf16 v[96:99], v[182:185], v[202:205], v[96:99]
	v_mfma_f32_16x16x32_bf16 v[84:87], v[164:167], v[210:213], v[84:87]
	v_mfma_f32_16x16x32_bf16 v[80:83], v[182:185], v[210:213], v[80:83]
	v_mfma_f32_16x16x32_bf16 v[68:71], v[164:167], v[218:221], v[68:71]
	v_mfma_f32_16x16x32_bf16 v[64:67], v[182:185], v[218:221], v[64:67]
	s_barrier
	s_add_i32 s49, s39, s26
	v_lshl_add_u64 v[172:173], s[20:21], 0, v[146:147]
	s_mov_b32 m0, s49
	s_setprio 2
	ds_read_b128 v[190:193], v179 offset:16384
	ds_read_b128 v[194:197], v179 offset:17408
	ds_read_b128 v[198:201], v179 offset:18432
	ds_read_b128 v[202:205], v179 offset:19456
	ds_read_b128 v[206:209], v179 offset:20480
	ds_read_b128 v[210:213], v179 offset:21504
	ds_read_b128 v[214:217], v179 offset:22528
	ds_read_b128 v[218:221], v179 offset:23552
	s_setprio 0
	global_load_lds_dwordx4 v[172:173], off
	s_add_i32 m0, s49, 0x2000
	s_add_u32 s50, s20, 0x160000
	v_lshl_add_u64 v[186:187], s[20:21], 0, v[150:151]
	s_addc_u32 s51, s21, 0
	s_add_i32 s49, s40, s26
	global_load_lds_dwordx4 v[186:187], off
	v_lshl_add_u64 v[222:223], s[50:51], 0, v[146:147]
	s_mov_b32 m0, s49
	v_lshl_add_u64 v[224:225], s[22:23], 0, v[148:149]
	global_load_lds_dwordx4 v[222:223], off
	v_lshl_add_u64 v[222:223], s[50:51], 0, v[150:151]
	s_add_i32 m0, s49, 0x2000
	s_nop 0
	global_load_lds_dwordx4 v[222:223], off
	v_lshl_add_u64 v[222:223], s[22:23], 0, v[144:145]
	s_mov_b32 m0, s27
	s_nop 0
	global_load_lds_dwordx4 v[222:223], off
	s_mov_b32 m0, s28
	s_nop 0
	global_load_lds_dwordx4 v[224:225], off
	s_waitcnt vmcnt(8)
	s_waitcnt lgkmcnt(0)
	s_barrier
	v_mfma_f32_16x16x32_bf16 v[60:63], v[128:131], v[190:193], v[60:63]
	v_mfma_f32_16x16x32_bf16 v[56:59], v[136:139], v[190:193], v[56:59]
	v_mfma_f32_16x16x32_bf16 v[44:47], v[128:131], v[198:201], v[44:47]
	v_mfma_f32_16x16x32_bf16 v[40:43], v[136:139], v[198:201], v[40:43]
	v_mfma_f32_16x16x32_bf16 v[28:31], v[128:131], v[206:209], v[28:31]
	v_mfma_f32_16x16x32_bf16 v[24:27], v[136:139], v[206:209], v[24:27]
	v_mfma_f32_16x16x32_bf16 v[12:15], v[128:131], v[214:217], v[12:15]
	v_mfma_f32_16x16x32_bf16 v[8:11], v[136:139], v[214:217], v[8:11]
	v_mfma_f32_16x16x32_bf16 v[60:63], v[132:135], v[194:197], v[60:63]
	v_mfma_f32_16x16x32_bf16 v[56:59], v[140:143], v[194:197], v[56:59]
	v_mfma_f32_16x16x32_bf16 v[44:47], v[132:135], v[202:205], v[44:47]
	v_mfma_f32_16x16x32_bf16 v[40:43], v[140:143], v[202:205], v[40:43]
	v_mfma_f32_16x16x32_bf16 v[28:31], v[132:135], v[210:213], v[28:31]
	v_mfma_f32_16x16x32_bf16 v[24:27], v[140:143], v[210:213], v[24:27]
	v_mfma_f32_16x16x32_bf16 v[12:15], v[132:135], v[218:221], v[12:15]
	v_mfma_f32_16x16x32_bf16 v[8:11], v[140:143], v[218:221], v[8:11]
	v_mfma_f32_16x16x32_bf16 v[52:55], v[160:163], v[190:193], v[52:55]
	v_mfma_f32_16x16x32_bf16 v[48:51], v[168:171], v[190:193], v[48:51]
	v_mfma_f32_16x16x32_bf16 v[36:39], v[160:163], v[198:201], v[36:39]
	v_mfma_f32_16x16x32_bf16 v[32:35], v[168:171], v[198:201], v[32:35]
	v_mfma_f32_16x16x32_bf16 v[20:23], v[160:163], v[206:209], v[20:23]
	v_mfma_f32_16x16x32_bf16 v[16:19], v[168:171], v[206:209], v[16:19]
	v_mfma_f32_16x16x32_bf16 v[4:7], v[160:163], v[214:217], v[4:7]
	v_mfma_f32_16x16x32_bf16 v[0:3], v[168:171], v[214:217], v[0:3]
	v_mfma_f32_16x16x32_bf16 v[52:55], v[164:167], v[194:197], v[52:55]
	v_mfma_f32_16x16x32_bf16 v[48:51], v[182:185], v[194:197], v[48:51]
	v_mfma_f32_16x16x32_bf16 v[36:39], v[164:167], v[202:205], v[36:39]
	v_mfma_f32_16x16x32_bf16 v[32:35], v[182:185], v[202:205], v[32:35]
	v_mfma_f32_16x16x32_bf16 v[20:23], v[164:167], v[210:213], v[20:23]
	v_mfma_f32_16x16x32_bf16 v[16:19], v[182:185], v[210:213], v[16:19]
	v_mfma_f32_16x16x32_bf16 v[4:7], v[164:167], v[218:221], v[4:7]
	v_mfma_f32_16x16x32_bf16 v[0:3], v[182:185], v[218:221], v[0:3]
	s_barrier
	s_add_i32 s49, 0, 0x18000
	s_add_i32 s50, 0, 0x1c000
	v_add_u32_e32 v140, s49, v175
	v_add_u32_e32 v181, s50, v175
	s_setprio 2
	ds_read_b128 v[128:131], v140
	ds_read_b128 v[132:135], v140 offset:1024
	ds_read_b128 v[136:139], v140 offset:2048
	ds_read_b128 v[140:143], v140 offset:3072
	ds_read_b128 v[160:163], v181
	ds_read_b128 v[164:167], v181 offset:1024
	ds_read_b128 v[168:171], v181 offset:2048
	ds_read_b128 v[182:185], v181 offset:3072
	s_add_u32 s22, s22, 0x160000
	s_addc_u32 s23, s23, 0
	s_mov_b32 m0, s29
	v_lshl_add_u64 v[226:227], s[22:23], 0, v[144:145]
	ds_read_b128 v[190:193], v179 offset:32768
	ds_read_b128 v[194:197], v179 offset:33792
	ds_read_b128 v[198:201], v179 offset:34816
	ds_read_b128 v[202:205], v179 offset:35840
	ds_read_b128 v[206:209], v179 offset:36864
	ds_read_b128 v[210:213], v179 offset:37888
	ds_read_b128 v[214:217], v179 offset:38912
	ds_read_b128 v[218:221], v179 offset:39936
	s_setprio 0
	global_load_lds_dwordx4 v[226:227], off
	v_lshl_add_u64 v[226:227], s[22:23], 0, v[148:149]
	s_mov_b32 m0, s30
	s_nop 0
	global_load_lds_dwordx4 v[226:227], off
	s_waitcnt vmcnt(8)
	s_waitcnt lgkmcnt(0)
	s_barrier
	v_mfma_f32_16x16x32_bf16 v[124:127], v[128:131], v[190:193], v[124:127]
	v_mfma_f32_16x16x32_bf16 v[120:123], v[136:139], v[190:193], v[120:123]
	v_mfma_f32_16x16x32_bf16 v[108:111], v[128:131], v[198:201], v[108:111]
	v_mfma_f32_16x16x32_bf16 v[104:107], v[136:139], v[198:201], v[104:107]
	v_mfma_f32_16x16x32_bf16 v[92:95], v[128:131], v[206:209], v[92:95]
	v_mfma_f32_16x16x32_bf16 v[88:91], v[136:139], v[206:209], v[88:91]
	v_mfma_f32_16x16x32_bf16 v[76:79], v[128:131], v[214:217], v[76:79]
	v_mfma_f32_16x16x32_bf16 v[72:75], v[136:139], v[214:217], v[72:75]
	v_mfma_f32_16x16x32_bf16 v[124:127], v[132:135], v[194:197], v[124:127]
	v_mfma_f32_16x16x32_bf16 v[120:123], v[140:143], v[194:197], v[120:123]
	v_mfma_f32_16x16x32_bf16 v[108:111], v[132:135], v[202:205], v[108:111]
	v_mfma_f32_16x16x32_bf16 v[104:107], v[140:143], v[202:205], v[104:107]
	v_mfma_f32_16x16x32_bf16 v[92:95], v[132:135], v[210:213], v[92:95]
	v_mfma_f32_16x16x32_bf16 v[88:91], v[140:143], v[210:213], v[88:91]
	v_mfma_f32_16x16x32_bf16 v[76:79], v[132:135], v[218:221], v[76:79]
	v_mfma_f32_16x16x32_bf16 v[72:75], v[140:143], v[218:221], v[72:75]
	v_mfma_f32_16x16x32_bf16 v[116:119], v[160:163], v[190:193], v[116:119]
	v_mfma_f32_16x16x32_bf16 v[112:115], v[168:171], v[190:193], v[112:115]
	v_mfma_f32_16x16x32_bf16 v[100:103], v[160:163], v[198:201], v[100:103]
	v_mfma_f32_16x16x32_bf16 v[96:99], v[168:171], v[198:201], v[96:99]
	v_mfma_f32_16x16x32_bf16 v[84:87], v[160:163], v[206:209], v[84:87]
	v_mfma_f32_16x16x32_bf16 v[80:83], v[168:171], v[206:209], v[80:83]
	v_mfma_f32_16x16x32_bf16 v[68:71], v[160:163], v[214:217], v[68:71]
	v_mfma_f32_16x16x32_bf16 v[64:67], v[168:171], v[214:217], v[64:67]
	v_mfma_f32_16x16x32_bf16 v[116:119], v[164:167], v[194:197], v[116:119]
	v_mfma_f32_16x16x32_bf16 v[112:115], v[182:185], v[194:197], v[112:115]
	v_mfma_f32_16x16x32_bf16 v[100:103], v[164:167], v[202:205], v[100:103]
	v_mfma_f32_16x16x32_bf16 v[96:99], v[182:185], v[202:205], v[96:99]
	v_mfma_f32_16x16x32_bf16 v[84:87], v[164:167], v[210:213], v[84:87]
	v_mfma_f32_16x16x32_bf16 v[80:83], v[182:185], v[210:213], v[80:83]
	v_mfma_f32_16x16x32_bf16 v[68:71], v[164:167], v[218:221], v[68:71]
	v_mfma_f32_16x16x32_bf16 v[64:67], v[182:185], v[218:221], v[64:67]
	s_barrier
	s_add_i32 s22, s49, s26
	v_lshl_add_u64 v[172:173], v[172:173], 0, s[10:11]
	s_mov_b32 m0, s22
	s_setprio 2
	ds_read_b128 v[190:193], v179 offset:49152
	ds_read_b128 v[194:197], v179 offset:50176
	ds_read_b128 v[198:201], v179 offset:51200
	ds_read_b128 v[202:205], v179 offset:52224
	ds_read_b128 v[206:209], v179 offset:53248
	ds_read_b128 v[210:213], v179 offset:54272
	ds_read_b128 v[214:217], v179 offset:55296
	ds_read_b128 v[218:221], v179 offset:56320
	s_setprio 0
	global_load_lds_dwordx4 v[172:173], off
	s_add_i32 m0, s22, 0x2000
	s_add_u32 s20, s20, 0x160080
	v_lshl_add_u64 v[172:173], v[186:187], 0, s[10:11]
	s_addc_u32 s21, s21, 0
	s_add_i32 s22, s50, s26
	global_load_lds_dwordx4 v[172:173], off
	v_lshl_add_u64 v[172:173], s[20:21], 0, v[146:147]
	s_mov_b32 m0, s22
	s_nop 0
	global_load_lds_dwordx4 v[172:173], off
	v_lshl_add_u64 v[172:173], s[20:21], 0, v[150:151]
	s_add_i32 m0, s22, 0x2000
	s_nop 0
	global_load_lds_dwordx4 v[172:173], off
	v_lshl_add_u64 v[172:173], v[222:223], 0, s[10:11]
	s_mov_b32 m0, s35
	s_nop 0
	global_load_lds_dwordx4 v[172:173], off
	v_lshl_add_u64 v[172:173], v[224:225], 0, s[10:11]
	s_mov_b32 m0, s36
	s_nop 0
	global_load_lds_dwordx4 v[172:173], off
	s_waitcnt vmcnt(8)
	s_waitcnt lgkmcnt(0)
	s_barrier
	v_mfma_f32_16x16x32_bf16 v[60:63], v[128:131], v[190:193], v[60:63]
	v_mfma_f32_16x16x32_bf16 v[56:59], v[136:139], v[190:193], v[56:59]
	v_mfma_f32_16x16x32_bf16 v[44:47], v[128:131], v[198:201], v[44:47]
	v_mfma_f32_16x16x32_bf16 v[40:43], v[136:139], v[198:201], v[40:43]
	v_mfma_f32_16x16x32_bf16 v[28:31], v[128:131], v[206:209], v[28:31]
	v_mfma_f32_16x16x32_bf16 v[24:27], v[136:139], v[206:209], v[24:27]
	v_mfma_f32_16x16x32_bf16 v[12:15], v[128:131], v[214:217], v[12:15]
	v_mfma_f32_16x16x32_bf16 v[8:11], v[136:139], v[214:217], v[8:11]
	v_mfma_f32_16x16x32_bf16 v[60:63], v[132:135], v[194:197], v[60:63]
	v_mfma_f32_16x16x32_bf16 v[56:59], v[140:143], v[194:197], v[56:59]
	v_mfma_f32_16x16x32_bf16 v[44:47], v[132:135], v[202:205], v[44:47]
	v_mfma_f32_16x16x32_bf16 v[40:43], v[140:143], v[202:205], v[40:43]
	v_mfma_f32_16x16x32_bf16 v[28:31], v[132:135], v[210:213], v[28:31]
	v_mfma_f32_16x16x32_bf16 v[24:27], v[140:143], v[210:213], v[24:27]
	v_mfma_f32_16x16x32_bf16 v[12:15], v[132:135], v[218:221], v[12:15]
	v_mfma_f32_16x16x32_bf16 v[8:11], v[140:143], v[218:221], v[8:11]
	v_mfma_f32_16x16x32_bf16 v[52:55], v[160:163], v[190:193], v[52:55]
	v_mfma_f32_16x16x32_bf16 v[48:51], v[168:171], v[190:193], v[48:51]
	v_mfma_f32_16x16x32_bf16 v[36:39], v[160:163], v[198:201], v[36:39]
	v_mfma_f32_16x16x32_bf16 v[32:35], v[168:171], v[198:201], v[32:35]
	v_mfma_f32_16x16x32_bf16 v[20:23], v[160:163], v[206:209], v[20:23]
	v_mfma_f32_16x16x32_bf16 v[16:19], v[168:171], v[206:209], v[16:19]
	v_mfma_f32_16x16x32_bf16 v[4:7], v[160:163], v[214:217], v[4:7]
	v_mfma_f32_16x16x32_bf16 v[0:3], v[168:171], v[214:217], v[0:3]
	v_mfma_f32_16x16x32_bf16 v[52:55], v[164:167], v[194:197], v[52:55]
	v_mfma_f32_16x16x32_bf16 v[48:51], v[182:185], v[194:197], v[48:51]
	v_mfma_f32_16x16x32_bf16 v[36:39], v[164:167], v[202:205], v[36:39]
	v_mfma_f32_16x16x32_bf16 v[32:35], v[182:185], v[202:205], v[32:35]
	v_mfma_f32_16x16x32_bf16 v[20:23], v[164:167], v[210:213], v[20:23]
	v_mfma_f32_16x16x32_bf16 v[16:19], v[182:185], v[210:213], v[16:19]
	v_mfma_f32_16x16x32_bf16 v[4:7], v[164:167], v[218:221], v[4:7]
	v_mfma_f32_16x16x32_bf16 v[0:3], v[182:185], v[218:221], v[0:3]
	s_barrier
	s_add_i32 s48, s48, 2
	s_add_u32 s18, s18, 0x100
	s_addc_u32 s19, s19, 0
	s_add_u32 s46, s46, 0x100
	s_addc_u32 s47, s47, 0
	s_cmpk_gt_u32 s48, 0x55
	s_cbranch_scc0 .LBB0_1624
	s_and_b64 vcc, exec, s[12:13]
	s_cbranch_vccz .LBB0_1627
	s_barrier
